# xattn K/V staging: coalesced global loads (8 lanes of a row cover one 128-B line per instruction; LDS image unchanged)
# speedup vs baseline: 1.0079x; 1.0079x over previous
.LBB0_750:
	s_or_b64 exec, exec, s[4:5]
	v_lshlrev_b32_e32 v148, 12, v154
	v_mov_b32_e32 v149, 0
	v_and_b32_e32 v2, 7, v223
	v_lshl_add_u64 v[0:1], s[30:31], 0, v[148:149]
	s_mov_b64 s[4:5], 0x2a00000
	s_ashr_i32 s3, s26, 31
	s_ashr_i32 s27, s2, 31
	v_lshl_add_u64 v[150:151], v[0:1], 0, s[4:5]
	v_lshlrev_b32_e32 v0, 3, v2
	v_lshlrev_b32_e32 v1, 4, v2
	v_mul_u32_u24_e32 v2, 0x230, v154
	s_add_u32 s6, s30, 0x2f00000
	s_movk_i32 s4, 0x230
	v_add3_u32 v172, 0, v1, v2
	v_or_b32_e32 v2, v178, v152
	v_and_or_b32 v3, v153, 12, v177
	s_addc_u32 s7, s31, 0
	v_lshlrev_b32_e32 v177, 1, v3
	v_mad_u32_u24 v2, v2, s4, 0
	v_mov_b32_e32 v181, v149
	v_mul_u32_u24_e32 v1, 0x230, v176
	s_add_u32 s12, s30, 0xa000000
	v_add_u32_e32 v186, v2, v177
	v_add_u32_e32 v187, 0x10680, v2
	v_add_u32_e32 v188, 0x11800, v2
	v_add_u32_e32 v189, 0x12980, v2
	v_add_u32_e32 v190, 0x13b00, v2
	v_add_u32_e32 v191, 0x14c80, v2
	v_add_u32_e32 v192, 0x15e00, v2
	v_add_u32_e32 v193, 0x16f80, v2
	v_add_u32_e32 v194, 0x18100, v2
	v_add_u32_e32 v195, 0x19280, v2
	v_add_u32_e32 v196, 0x1a400, v2
	v_add_u32_e32 v197, 0x1b580, v2
	v_add_u32_e32 v198, 0x1c700, v2
	v_add_u32_e32 v199, 0x1d880, v2
	v_add_u32_e32 v200, 0x1ea00, v2
	v_add_u32_e32 v201, 0x1fb80, v2
	v_add_u32_e32 v202, 0x20d00, v2
	v_add_u32_e32 v203, 0x21e80, v2
	v_lshl_add_u64 v[2:3], s[30:31], 0, v[180:181]
	s_mov_b64 s[4:5], 0x8000080
	v_lshlrev_b32_e32 v148, 1, v0
	v_mbcnt_lo_u32_b32 v0, -1, 0
	s_mov_b32 s11, 0
	v_add_u32_e32 v173, 0x11800, v172
	v_add_u32_e32 v174, 0x11880, v172
	v_add_u32_e32 v175, 0x11900, v172
	v_add_u32_e32 v179, 0x11980, v172
	v_add_u32_e32 v182, 0x1a400, v172
	v_add_u32_e32 v183, 0x1a480, v172
	v_add_u32_e32 v184, 0x1a500, v172
	v_add_u32_e32 v185, 0x1a580, v172
	s_addc_u32 s13, s31, 0
	v_or_b32_e32 v204, 64, v177
	v_or_b32_e32 v205, 0x80, v177
	v_or_b32_e32 v206, 0xc0, v177
	v_or_b32_e32 v207, 0x100, v177
	v_or_b32_e32 v208, 0x140, v177
	v_or_b32_e32 v209, 0x180, v177
	v_or_b32_e32 v210, 0x1c0, v177
	v_add3_u32 v211, v1, v180, 0
	v_lshl_add_u64 v[152:153], v[2:3], 0, s[4:5]
	s_mov_b64 s[14:15], 0x100
	v_mov_b64_e32 v[154:155], 0x100
	v_mov_b64_e32 v[156:157], 0xff
	s_mov_b64 s[16:17], 0x40000
	s_mov_b32 s34, 0x40000
	s_mov_b64 s[18:19], 0x80000
	s_mov_b32 s35, 0x80000
	s_mov_b64 s[36:37], 0xc0000
	s_mov_b32 s48, 0xc0000
	v_mov_b32_e32 v180, 0x358637bd
	s_mov_b32 s49, 0x800000
	s_mov_b32 s50, 0xff800000
	s_mov_b64 s[38:39], 0x40800
	s_mov_b64 s[40:41], 0x80800
	s_mov_b64 s[44:45], 0xc0800
	v_lshlrev_b32_e32 v158, 1, v178
	v_mbcnt_hi_u32_b32 v178, -1, v0
	s_mov_b32 s51, 0
	s_barrier
	s_branch .LBB0_752

.LBB0_759:
	s_lshl_b32 s4, s53, 2
	s_or_b32 s54, s4, s52
	s_ashr_i32 s4, s54, 6
	s_ashr_i32 s5, s4, 31
	s_and_b32 s56, s52, 3
	s_lshl_b64 s[46:47], s[4:5], 20
	v_lshl_add_u64 v[0:1], v[150:151], 0, s[46:47]
	s_lshl_b32 s10, s56, 9
	v_lshl_add_u64 v[0:1], v[0:1], 0, s[10:11]
	v_readfirstlane_b32 s46, v223
	v_lshl_add_u64 v[160:161], v[0:1], 0, v[148:149]
	s_lshr_b32 s58, s46, 1
	s_lshl_b32 s59, s54, 6
	v_add_co_u32_e32 v168, vcc, s34, v160
	s_and_b32 s54, s58, 0x7fffffe0
	s_and_b32 s58, s59, 0xf00
	v_addc_co_u32_e32 v169, vcc, 0, v161, vcc
	s_lshl_b64 s[4:5], s[4:5], 12
	v_or_b32_e32 v66, s58, v176
	v_add_co_u32_e32 v164, vcc, s35, v160
	s_mov_b32 s55, s11
	v_or_b32_e32 v66, s4, v66
	v_mov_b32_e32 v67, s5
	v_addc_co_u32_e32 v165, vcc, 0, v161, vcc
	v_lshl_add_u64 v[66:67], v[66:67], 0, s[54:55]
	v_add_co_u32_e32 v166, vcc, s48, v160
	v_lshlrev_b64 v[68:69], 6, v[66:67]
	v_lshl_add_u64 v[0:1], v[160:161], 0, s[16:17]
	v_lshl_add_u64 v[46:47], v[160:161], 0, s[18:19]
	v_addc_co_u32_e32 v167, vcc, 0, v161, vcc
	v_lshlrev_b64 v[162:163], 11, v[66:67]
	v_lshl_add_u64 v[66:67], s[6:7], 0, v[68:69]
	global_load_dwordx4 v[2:5], v[160:161], off offset:384
	global_load_dwordx4 v[6:9], v[160:161], off offset:256
	global_load_dwordx4 v[10:13], v[160:161], off offset:128
	global_load_dwordx4 v[14:17], v[160:161], off
	global_load_dwordx4 v[18:21], v[0:1], off offset:256
	global_load_dwordx4 v[22:25], v[0:1], off offset:128
	global_load_dwordx4 v[26:29], v[168:169], off
	global_load_dwordx4 v[30:33], v[164:165], off
	global_load_dwordx4 v[34:37], v[46:47], off offset:384
	global_load_dwordx4 v[38:41], v[46:47], off offset:256
	global_load_dwordx4 v[42:45], v[0:1], off offset:384
	s_nop 0
	global_load_dwordx4 v[46:49], v[46:47], off offset:128
	v_lshl_add_u64 v[0:1], v[160:161], 0, s[36:37]
	global_load_dwordx4 v[50:53], v[166:167], off
	global_load_dwordx4 v[54:57], v[0:1], off offset:128
	global_load_dwordx4 v[58:61], v[0:1], off offset:256
	global_load_dwordx4 v[62:65], v[0:1], off offset:384
	s_mov_b32 s57, s11
	s_lshl_b32 s46, s56, 8
	s_lshl_b32 s56, s56, 4
	v_lshl_add_u64 v[68:69], s[8:9], 0, v[68:69]
	global_load_dwordx4 v[136:139], v[66:67], off offset:32
	global_load_dwordx4 v[140:143], v[66:67], off offset:16
	global_load_dwordx4 v[144:147], v[66:67], off
	v_lshl_add_u64 v[68:69], v[68:69], 0, s[56:57]
	global_load_dwordx4 v[132:135], v[66:67], off offset:48
	global_load_dwordx4 v[128:131], v[68:69], off
	v_mov_b32_e32 v0, 0
	v_or_b32_e32 v70, s10, v162
	v_mov_b32_e32 v71, v163
	s_mov_b32 s47, 0
	v_lshl_add_u64 v[170:171], v[152:153], 0, v[70:71]
	s_waitcnt vmcnt(17)
	ds_write_b128 v172, v[14:17]
	ds_write_b128 v172, v[10:13] offset:128
	ds_write_b128 v172, v[6:9] offset:256
	ds_write_b128 v172, v[2:5] offset:384
	s_waitcnt vmcnt(14)
	ds_write_b128 v172, v[26:29] offset:35840
	ds_write_b128 v172, v[22:25] offset:35968
	ds_write_b128 v172, v[18:21] offset:36096
	s_waitcnt vmcnt(10)
	ds_write_b128 v172, v[42:45] offset:36224
	ds_write_b128 v173, v[30:33]
	s_waitcnt vmcnt(9)
	ds_write_b128 v174, v[46:49]
	ds_write_b128 v175, v[38:41]
	ds_write_b128 v179, v[34:37]
	s_waitcnt vmcnt(8)
	ds_write_b128 v182, v[50:53]
	s_waitcnt vmcnt(7)
	ds_write_b128 v183, v[54:57]
	s_waitcnt vmcnt(6)
	ds_write_b128 v184, v[58:61]
	s_waitcnt vmcnt(5)
	ds_write_b128 v185, v[62:65]
	s_waitcnt lgkmcnt(0)
	s_barrier
.LBB0_760:
	v_add_u32_e32 v181, 0x11800, v211
	v_add_u32_e32 v220, 0x15e00, v211
	v_add_u32_e32 v221, 0x1a400, v211
	v_add_u32_e32 v222, 0x1ea00, v211
	global_load_dwordx4 v[212:215], v[170:171], off offset:-128
	global_load_dwordx4 v[216:219], v[170:171], off offset:-96
	global_load_dwordx4 v[248:251], v[170:171], off offset:-64
	ds_read_b128 v[224:227], v211
	ds_read_b128 v[228:231], v211 offset:17920
	ds_read_b128 v[232:235], v211 offset:35840
	ds_read_b128 v[236:239], v211 offset:53760
	ds_read_b128 v[240:243], v181
	ds_read_b128 v[244:247], v220
	s_waitcnt vmcnt(2) lgkmcnt(5)
	v_mfma_f32_32x32x16_bf16 v[112:127], v[224:227], v[212:215], 0
	ds_read_b128 v[224:227], v221
	s_waitcnt lgkmcnt(5)
	v_mfma_f32_32x32x16_bf16 v[96:111], v[228:231], v[212:215], 0
	ds_read_b128 v[228:231], v222
	s_waitcnt lgkmcnt(5)
	v_mfma_f32_32x32x16_bf16 v[80:95], v[232:235], v[212:215], 0
	ds_read_b128 v[232:235], v211 offset:32
	s_waitcnt lgkmcnt(5)
	v_mfma_f32_32x32x16_bf16 v[64:79], v[236:239], v[212:215], 0
	ds_read_b128 v[236:239], v211 offset:17952
	s_waitcnt lgkmcnt(5)
	v_mfma_f32_32x32x16_bf16 v[48:63], v[240:243], v[212:215], 0
	ds_read_b128 v[240:243], v211 offset:35872
	s_waitcnt lgkmcnt(5)
	v_mfma_f32_32x32x16_bf16 v[32:47], v[244:247], v[212:215], 0
	ds_read_b128 v[244:247], v211 offset:53792
	s_waitcnt lgkmcnt(5)
	v_mfma_f32_32x32x16_bf16 v[16:31], v[224:227], v[212:215], 0
	ds_read_b128 v[224:227], v181 offset:32
	s_waitcnt lgkmcnt(5)
	v_mfma_f32_32x32x16_bf16 v[0:15], v[228:231], v[212:215], 0
	ds_read_b128 v[228:231], v220 offset:32
	global_load_dwordx4 v[212:215], v[170:171], off offset:-32
	s_waitcnt vmcnt(2) lgkmcnt(5)
	v_mfma_f32_32x32x16_bf16 v[112:127], v[232:235], v[216:219], v[112:127]
	ds_read_b128 v[232:235], v221 offset:32
	s_waitcnt lgkmcnt(5)
	v_mfma_f32_32x32x16_bf16 v[96:111], v[236:239], v[216:219], v[96:111]
	ds_read_b128 v[236:239], v222 offset:32
	s_waitcnt lgkmcnt(5)
	v_mfma_f32_32x32x16_bf16 v[80:95], v[240:243], v[216:219], v[80:95]
	ds_read_b128 v[240:243], v211 offset:64
	s_waitcnt lgkmcnt(5)
	v_mfma_f32_32x32x16_bf16 v[64:79], v[244:247], v[216:219], v[64:79]
	ds_read_b128 v[244:247], v211 offset:17984
	s_waitcnt lgkmcnt(5)
	v_mfma_f32_32x32x16_bf16 v[48:63], v[224:227], v[216:219], v[48:63]
	ds_read_b128 v[224:227], v211 offset:35904
	s_waitcnt lgkmcnt(5)
	v_mfma_f32_32x32x16_bf16 v[32:47], v[228:231], v[216:219], v[32:47]
	ds_read_b128 v[228:231], v211 offset:53824
	s_waitcnt lgkmcnt(5)
	v_mfma_f32_32x32x16_bf16 v[16:31], v[232:235], v[216:219], v[16:31]
	ds_read_b128 v[232:235], v181 offset:64
	s_waitcnt lgkmcnt(5)
	v_mfma_f32_32x32x16_bf16 v[0:15], v[236:239], v[216:219], v[0:15]
	ds_read_b128 v[236:239], v220 offset:64
	global_load_dwordx4 v[216:219], v[170:171], off
	s_waitcnt vmcnt(2) lgkmcnt(5)
	v_mfma_f32_32x32x16_bf16 v[112:127], v[240:243], v[248:251], v[112:127]
	ds_read_b128 v[240:243], v221 offset:64
	s_waitcnt lgkmcnt(5)
	v_mfma_f32_32x32x16_bf16 v[96:111], v[244:247], v[248:251], v[96:111]
	ds_read_b128 v[244:247], v222 offset:64
	s_waitcnt lgkmcnt(5)
	v_mfma_f32_32x32x16_bf16 v[80:95], v[224:227], v[248:251], v[80:95]
	ds_read_b128 v[224:227], v211 offset:96
	s_waitcnt lgkmcnt(5)
	v_mfma_f32_32x32x16_bf16 v[64:79], v[228:231], v[248:251], v[64:79]
	ds_read_b128 v[228:231], v211 offset:18016
	s_waitcnt lgkmcnt(5)
	v_mfma_f32_32x32x16_bf16 v[48:63], v[232:235], v[248:251], v[48:63]
	ds_read_b128 v[232:235], v211 offset:35936
	s_waitcnt lgkmcnt(5)
	v_mfma_f32_32x32x16_bf16 v[32:47], v[236:239], v[248:251], v[32:47]
	ds_read_b128 v[236:239], v211 offset:53856
	s_waitcnt lgkmcnt(5)
	v_mfma_f32_32x32x16_bf16 v[16:31], v[240:243], v[248:251], v[16:31]
	ds_read_b128 v[240:243], v181 offset:96
	s_waitcnt lgkmcnt(5)
	v_mfma_f32_32x32x16_bf16 v[0:15], v[244:247], v[248:251], v[0:15]
	ds_read_b128 v[244:247], v220 offset:96
	global_load_dwordx4 v[248:251], v[170:171], off offset:32
	s_waitcnt vmcnt(2) lgkmcnt(5)
	v_mfma_f32_32x32x16_bf16 v[112:127], v[224:227], v[212:215], v[112:127]
	ds_read_b128 v[224:227], v221 offset:96
	s_waitcnt lgkmcnt(5)
	v_mfma_f32_32x32x16_bf16 v[96:111], v[228:231], v[212:215], v[96:111]
	ds_read_b128 v[228:231], v222 offset:96
	s_waitcnt lgkmcnt(5)
	v_mfma_f32_32x32x16_bf16 v[80:95], v[232:235], v[212:215], v[80:95]
	ds_read_b128 v[232:235], v211 offset:128
	s_waitcnt lgkmcnt(5)
	v_mfma_f32_32x32x16_bf16 v[64:79], v[236:239], v[212:215], v[64:79]
	ds_read_b128 v[236:239], v211 offset:18048
	s_waitcnt lgkmcnt(5)
	v_mfma_f32_32x32x16_bf16 v[48:63], v[240:243], v[212:215], v[48:63]
	ds_read_b128 v[240:243], v211 offset:35968
	s_waitcnt lgkmcnt(5)
	v_mfma_f32_32x32x16_bf16 v[32:47], v[244:247], v[212:215], v[32:47]
	ds_read_b128 v[244:247], v211 offset:53888
	s_waitcnt lgkmcnt(5)
	v_mfma_f32_32x32x16_bf16 v[16:31], v[224:227], v[212:215], v[16:31]
	ds_read_b128 v[224:227], v181 offset:128
	s_waitcnt lgkmcnt(5)
	v_mfma_f32_32x32x16_bf16 v[0:15], v[228:231], v[212:215], v[0:15]
	ds_read_b128 v[228:231], v220 offset:128
	global_load_dwordx4 v[212:215], v[170:171], off offset:64
	s_waitcnt vmcnt(2) lgkmcnt(5)
	v_mfma_f32_32x32x16_bf16 v[112:127], v[232:235], v[216:219], v[112:127]
	ds_read_b128 v[232:235], v221 offset:128
	s_waitcnt lgkmcnt(5)
	v_mfma_f32_32x32x16_bf16 v[96:111], v[236:239], v[216:219], v[96:111]
	ds_read_b128 v[236:239], v222 offset:128
	s_waitcnt lgkmcnt(5)
	v_mfma_f32_32x32x16_bf16 v[80:95], v[240:243], v[216:219], v[80:95]
	ds_read_b128 v[240:243], v211 offset:160
	s_waitcnt lgkmcnt(5)
	v_mfma_f32_32x32x16_bf16 v[64:79], v[244:247], v[216:219], v[64:79]
	ds_read_b128 v[244:247], v211 offset:18080
	s_waitcnt lgkmcnt(5)
	v_mfma_f32_32x32x16_bf16 v[48:63], v[224:227], v[216:219], v[48:63]
	ds_read_b128 v[224:227], v211 offset:36000
	s_waitcnt lgkmcnt(5)
	v_mfma_f32_32x32x16_bf16 v[32:47], v[228:231], v[216:219], v[32:47]
	ds_read_b128 v[228:231], v211 offset:53920
	s_waitcnt lgkmcnt(5)
	v_mfma_f32_32x32x16_bf16 v[16:31], v[232:235], v[216:219], v[16:31]
	ds_read_b128 v[232:235], v181 offset:160
	s_waitcnt lgkmcnt(5)
	v_mfma_f32_32x32x16_bf16 v[0:15], v[236:239], v[216:219], v[0:15]
	ds_read_b128 v[236:239], v220 offset:160
	global_load_dwordx4 v[216:219], v[170:171], off offset:96
	s_waitcnt vmcnt(2) lgkmcnt(5)
	v_mfma_f32_32x32x16_bf16 v[112:127], v[240:243], v[248:251], v[112:127]
	ds_read_b128 v[240:243], v221 offset:160
	s_waitcnt lgkmcnt(5)
	v_mfma_f32_32x32x16_bf16 v[96:111], v[244:247], v[248:251], v[96:111]
	ds_read_b128 v[244:247], v222 offset:160
	s_waitcnt lgkmcnt(5)
	v_mfma_f32_32x32x16_bf16 v[80:95], v[224:227], v[248:251], v[80:95]
	ds_read_b128 v[224:227], v211 offset:192
	s_waitcnt lgkmcnt(5)
	v_mfma_f32_32x32x16_bf16 v[64:79], v[228:231], v[248:251], v[64:79]
	ds_read_b128 v[228:231], v211 offset:18112
	s_waitcnt lgkmcnt(5)
	v_mfma_f32_32x32x16_bf16 v[48:63], v[232:235], v[248:251], v[48:63]
	ds_read_b128 v[232:235], v211 offset:36032
	s_waitcnt lgkmcnt(5)
	v_mfma_f32_32x32x16_bf16 v[32:47], v[236:239], v[248:251], v[32:47]
	ds_read_b128 v[236:239], v211 offset:53952
	s_waitcnt lgkmcnt(5)
	v_mfma_f32_32x32x16_bf16 v[16:31], v[240:243], v[248:251], v[16:31]
	ds_read_b128 v[240:243], v181 offset:192
	s_waitcnt lgkmcnt(5)
	v_mfma_f32_32x32x16_bf16 v[0:15], v[244:247], v[248:251], v[0:15]
	ds_read_b128 v[244:247], v220 offset:192
	global_load_dwordx4 v[248:251], v[170:171], off offset:128
	s_waitcnt vmcnt(2) lgkmcnt(5)
	v_mfma_f32_32x32x16_bf16 v[112:127], v[224:227], v[212:215], v[112:127]
	ds_read_b128 v[224:227], v221 offset:192
	s_waitcnt lgkmcnt(5)
	v_mfma_f32_32x32x16_bf16 v[96:111], v[228:231], v[212:215], v[96:111]
	ds_read_b128 v[228:231], v222 offset:192
	s_waitcnt lgkmcnt(5)
	v_mfma_f32_32x32x16_bf16 v[80:95], v[232:235], v[212:215], v[80:95]
	ds_read_b128 v[232:235], v211 offset:224
	s_waitcnt lgkmcnt(5)
	v_mfma_f32_32x32x16_bf16 v[64:79], v[236:239], v[212:215], v[64:79]
	ds_read_b128 v[236:239], v211 offset:18144
	s_waitcnt lgkmcnt(5)
	v_mfma_f32_32x32x16_bf16 v[48:63], v[240:243], v[212:215], v[48:63]
	ds_read_b128 v[240:243], v211 offset:36064
	s_waitcnt lgkmcnt(5)
	v_mfma_f32_32x32x16_bf16 v[32:47], v[244:247], v[212:215], v[32:47]
	ds_read_b128 v[244:247], v211 offset:53984
	s_waitcnt lgkmcnt(5)
	v_mfma_f32_32x32x16_bf16 v[16:31], v[224:227], v[212:215], v[16:31]
	ds_read_b128 v[224:227], v181 offset:224
	s_waitcnt lgkmcnt(5)
	v_mfma_f32_32x32x16_bf16 v[0:15], v[228:231], v[212:215], v[0:15]
	ds_read_b128 v[228:231], v220 offset:224
	global_load_dwordx4 v[212:215], v[170:171], off offset:160
	s_waitcnt vmcnt(2) lgkmcnt(5)
	v_mfma_f32_32x32x16_bf16 v[112:127], v[232:235], v[216:219], v[112:127]
	ds_read_b128 v[232:235], v221 offset:224
	s_waitcnt lgkmcnt(5)
	v_mfma_f32_32x32x16_bf16 v[96:111], v[236:239], v[216:219], v[96:111]
	ds_read_b128 v[236:239], v222 offset:224
	s_waitcnt lgkmcnt(5)
	v_mfma_f32_32x32x16_bf16 v[80:95], v[240:243], v[216:219], v[80:95]
	ds_read_b128 v[240:243], v211 offset:256
	s_waitcnt lgkmcnt(5)
	v_mfma_f32_32x32x16_bf16 v[64:79], v[244:247], v[216:219], v[64:79]
	ds_read_b128 v[244:247], v211 offset:18176
	s_waitcnt lgkmcnt(5)
	v_mfma_f32_32x32x16_bf16 v[48:63], v[224:227], v[216:219], v[48:63]
	ds_read_b128 v[224:227], v211 offset:36096
	s_waitcnt lgkmcnt(5)
	v_mfma_f32_32x32x16_bf16 v[32:47], v[228:231], v[216:219], v[32:47]
	ds_read_b128 v[228:231], v211 offset:54016
	s_waitcnt lgkmcnt(5)
	v_mfma_f32_32x32x16_bf16 v[16:31], v[232:235], v[216:219], v[16:31]
	ds_read_b128 v[232:235], v181 offset:256
	s_waitcnt lgkmcnt(5)
	v_mfma_f32_32x32x16_bf16 v[0:15], v[236:239], v[216:219], v[0:15]
	ds_read_b128 v[236:239], v220 offset:256
	global_load_dwordx4 v[216:219], v[170:171], off offset:192
	s_waitcnt vmcnt(2) lgkmcnt(5)
	v_mfma_f32_32x32x16_bf16 v[112:127], v[240:243], v[248:251], v[112:127]
	ds_read_b128 v[240:243], v221 offset:256
	s_waitcnt lgkmcnt(5)
	v_mfma_f32_32x32x16_bf16 v[96:111], v[244:247], v[248:251], v[96:111]
	ds_read_b128 v[244:247], v222 offset:256
	s_waitcnt lgkmcnt(5)
	v_mfma_f32_32x32x16_bf16 v[80:95], v[224:227], v[248:251], v[80:95]
	ds_read_b128 v[224:227], v211 offset:288
	s_waitcnt lgkmcnt(5)
	v_mfma_f32_32x32x16_bf16 v[64:79], v[228:231], v[248:251], v[64:79]
	ds_read_b128 v[228:231], v211 offset:18208
	s_waitcnt lgkmcnt(5)
	v_mfma_f32_32x32x16_bf16 v[48:63], v[232:235], v[248:251], v[48:63]
	ds_read_b128 v[232:235], v211 offset:36128
	s_waitcnt lgkmcnt(5)
	v_mfma_f32_32x32x16_bf16 v[32:47], v[236:239], v[248:251], v[32:47]
	ds_read_b128 v[236:239], v211 offset:54048
	s_waitcnt lgkmcnt(5)
	v_mfma_f32_32x32x16_bf16 v[16:31], v[240:243], v[248:251], v[16:31]
	ds_read_b128 v[240:243], v181 offset:288
	s_waitcnt lgkmcnt(5)
	v_mfma_f32_32x32x16_bf16 v[0:15], v[244:247], v[248:251], v[0:15]
	ds_read_b128 v[244:247], v220 offset:288
	global_load_dwordx4 v[248:251], v[170:171], off offset:224
	s_waitcnt vmcnt(2) lgkmcnt(5)
	v_mfma_f32_32x32x16_bf16 v[112:127], v[224:227], v[212:215], v[112:127]
	ds_read_b128 v[224:227], v221 offset:288
	s_waitcnt lgkmcnt(5)
	v_mfma_f32_32x32x16_bf16 v[96:111], v[228:231], v[212:215], v[96:111]
	ds_read_b128 v[228:231], v222 offset:288
	s_waitcnt lgkmcnt(5)
	v_mfma_f32_32x32x16_bf16 v[80:95], v[232:235], v[212:215], v[80:95]
	ds_read_b128 v[232:235], v211 offset:320
	s_waitcnt lgkmcnt(5)
	v_mfma_f32_32x32x16_bf16 v[64:79], v[236:239], v[212:215], v[64:79]
	ds_read_b128 v[236:239], v211 offset:18240
	s_waitcnt lgkmcnt(5)
	v_mfma_f32_32x32x16_bf16 v[48:63], v[240:243], v[212:215], v[48:63]
	ds_read_b128 v[240:243], v211 offset:36160
	s_waitcnt lgkmcnt(5)
	v_mfma_f32_32x32x16_bf16 v[32:47], v[244:247], v[212:215], v[32:47]
	ds_read_b128 v[244:247], v211 offset:54080
	s_waitcnt lgkmcnt(5)
	v_mfma_f32_32x32x16_bf16 v[16:31], v[224:227], v[212:215], v[16:31]
	ds_read_b128 v[224:227], v181 offset:320
	s_waitcnt lgkmcnt(5)
	v_mfma_f32_32x32x16_bf16 v[0:15], v[228:231], v[212:215], v[0:15]
	ds_read_b128 v[228:231], v220 offset:320
	global_load_dwordx4 v[212:215], v[170:171], off offset:256
	s_waitcnt vmcnt(2) lgkmcnt(5)
	v_mfma_f32_32x32x16_bf16 v[112:127], v[232:235], v[216:219], v[112:127]
	ds_read_b128 v[232:235], v221 offset:320
	s_waitcnt lgkmcnt(5)
	v_mfma_f32_32x32x16_bf16 v[96:111], v[236:239], v[216:219], v[96:111]
	ds_read_b128 v[236:239], v222 offset:320
	s_waitcnt lgkmcnt(5)
	v_mfma_f32_32x32x16_bf16 v[80:95], v[240:243], v[216:219], v[80:95]
	ds_read_b128 v[240:243], v211 offset:352
	s_waitcnt lgkmcnt(5)
	v_mfma_f32_32x32x16_bf16 v[64:79], v[244:247], v[216:219], v[64:79]
	ds_read_b128 v[244:247], v211 offset:18272
	s_waitcnt lgkmcnt(5)
	v_mfma_f32_32x32x16_bf16 v[48:63], v[224:227], v[216:219], v[48:63]
	ds_read_b128 v[224:227], v211 offset:36192
	s_waitcnt lgkmcnt(5)
	v_mfma_f32_32x32x16_bf16 v[32:47], v[228:231], v[216:219], v[32:47]
	ds_read_b128 v[228:231], v211 offset:54112
	s_waitcnt lgkmcnt(5)
	v_mfma_f32_32x32x16_bf16 v[16:31], v[232:235], v[216:219], v[16:31]
	ds_read_b128 v[232:235], v181 offset:352
	s_waitcnt lgkmcnt(5)
	v_mfma_f32_32x32x16_bf16 v[0:15], v[236:239], v[216:219], v[0:15]
	ds_read_b128 v[236:239], v220 offset:352
	global_load_dwordx4 v[216:219], v[170:171], off offset:288
	s_waitcnt vmcnt(2) lgkmcnt(5)
	v_mfma_f32_32x32x16_bf16 v[112:127], v[240:243], v[248:251], v[112:127]
	ds_read_b128 v[240:243], v221 offset:352
	s_waitcnt lgkmcnt(5)
	v_mfma_f32_32x32x16_bf16 v[96:111], v[244:247], v[248:251], v[96:111]
	ds_read_b128 v[244:247], v222 offset:352
	s_waitcnt lgkmcnt(5)
	v_mfma_f32_32x32x16_bf16 v[80:95], v[224:227], v[248:251], v[80:95]
	ds_read_b128 v[224:227], v211 offset:384
	s_waitcnt lgkmcnt(5)
	v_mfma_f32_32x32x16_bf16 v[64:79], v[228:231], v[248:251], v[64:79]
	ds_read_b128 v[228:231], v211 offset:18304
	s_waitcnt lgkmcnt(5)
	v_mfma_f32_32x32x16_bf16 v[48:63], v[232:235], v[248:251], v[48:63]
	ds_read_b128 v[232:235], v211 offset:36224
	s_waitcnt lgkmcnt(5)
	v_mfma_f32_32x32x16_bf16 v[32:47], v[236:239], v[248:251], v[32:47]
	ds_read_b128 v[236:239], v211 offset:54144
	s_waitcnt lgkmcnt(5)
	v_mfma_f32_32x32x16_bf16 v[16:31], v[240:243], v[248:251], v[16:31]
	ds_read_b128 v[240:243], v181 offset:384
	s_waitcnt lgkmcnt(5)
	v_mfma_f32_32x32x16_bf16 v[0:15], v[244:247], v[248:251], v[0:15]
	ds_read_b128 v[244:247], v220 offset:384
	global_load_dwordx4 v[248:251], v[170:171], off offset:320
	s_waitcnt vmcnt(2) lgkmcnt(5)
	v_mfma_f32_32x32x16_bf16 v[112:127], v[224:227], v[212:215], v[112:127]
	ds_read_b128 v[224:227], v221 offset:384
	s_waitcnt lgkmcnt(5)
	v_mfma_f32_32x32x16_bf16 v[96:111], v[228:231], v[212:215], v[96:111]
	ds_read_b128 v[228:231], v222 offset:384
	s_waitcnt lgkmcnt(5)
	v_mfma_f32_32x32x16_bf16 v[80:95], v[232:235], v[212:215], v[80:95]
	ds_read_b128 v[232:235], v211 offset:416
	s_waitcnt lgkmcnt(5)
	v_mfma_f32_32x32x16_bf16 v[64:79], v[236:239], v[212:215], v[64:79]
	ds_read_b128 v[236:239], v211 offset:18336
	s_waitcnt lgkmcnt(5)
	v_mfma_f32_32x32x16_bf16 v[48:63], v[240:243], v[212:215], v[48:63]
	ds_read_b128 v[240:243], v211 offset:36256
	s_waitcnt lgkmcnt(5)
	v_mfma_f32_32x32x16_bf16 v[32:47], v[244:247], v[212:215], v[32:47]
	ds_read_b128 v[244:247], v211 offset:54176
	s_waitcnt lgkmcnt(5)
	v_mfma_f32_32x32x16_bf16 v[16:31], v[224:227], v[212:215], v[16:31]
	ds_read_b128 v[224:227], v181 offset:416
	s_waitcnt lgkmcnt(5)
	v_mfma_f32_32x32x16_bf16 v[0:15], v[228:231], v[212:215], v[0:15]
	ds_read_b128 v[228:231], v220 offset:416
	global_load_dwordx4 v[212:215], v[170:171], off offset:352
	s_waitcnt vmcnt(2) lgkmcnt(5)
	v_mfma_f32_32x32x16_bf16 v[112:127], v[232:235], v[216:219], v[112:127]
	ds_read_b128 v[232:235], v221 offset:416
	s_waitcnt lgkmcnt(5)
	v_mfma_f32_32x32x16_bf16 v[96:111], v[236:239], v[216:219], v[96:111]
	ds_read_b128 v[236:239], v222 offset:416
	s_waitcnt lgkmcnt(5)
	v_mfma_f32_32x32x16_bf16 v[80:95], v[240:243], v[216:219], v[80:95]
	ds_read_b128 v[240:243], v211 offset:448
	s_waitcnt lgkmcnt(5)
	v_mfma_f32_32x32x16_bf16 v[64:79], v[244:247], v[216:219], v[64:79]
	ds_read_b128 v[244:247], v211 offset:18368
	s_waitcnt lgkmcnt(5)
	v_mfma_f32_32x32x16_bf16 v[48:63], v[224:227], v[216:219], v[48:63]
	ds_read_b128 v[224:227], v211 offset:36288
	s_waitcnt lgkmcnt(5)
	v_mfma_f32_32x32x16_bf16 v[32:47], v[228:231], v[216:219], v[32:47]
	ds_read_b128 v[228:231], v211 offset:54208
	s_waitcnt lgkmcnt(5)
	v_mfma_f32_32x32x16_bf16 v[16:31], v[232:235], v[216:219], v[16:31]
	ds_read_b128 v[232:235], v181 offset:448
	s_waitcnt lgkmcnt(5)
	v_mfma_f32_32x32x16_bf16 v[0:15], v[236:239], v[216:219], v[0:15]
	ds_read_b128 v[236:239], v220 offset:448
	s_waitcnt vmcnt(1) lgkmcnt(5)
	v_mfma_f32_32x32x16_bf16 v[112:127], v[240:243], v[248:251], v[112:127]
	ds_read_b128 v[240:243], v221 offset:448
	s_waitcnt lgkmcnt(5)
	v_mfma_f32_32x32x16_bf16 v[96:111], v[244:247], v[248:251], v[96:111]
	ds_read_b128 v[244:247], v222 offset:448
	s_waitcnt lgkmcnt(5)
	v_mfma_f32_32x32x16_bf16 v[80:95], v[224:227], v[248:251], v[80:95]
	ds_read_b128 v[224:227], v211 offset:480
	s_waitcnt lgkmcnt(5)
	v_mfma_f32_32x32x16_bf16 v[64:79], v[228:231], v[248:251], v[64:79]
	ds_read_b128 v[228:231], v211 offset:18400
	s_waitcnt lgkmcnt(5)
	v_mfma_f32_32x32x16_bf16 v[48:63], v[232:235], v[248:251], v[48:63]
	ds_read_b128 v[232:235], v211 offset:36320
	s_waitcnt lgkmcnt(5)
	v_mfma_f32_32x32x16_bf16 v[32:47], v[236:239], v[248:251], v[32:47]
	ds_read_b128 v[236:239], v211 offset:54240
	s_waitcnt lgkmcnt(5)
	v_mfma_f32_32x32x16_bf16 v[16:31], v[240:243], v[248:251], v[16:31]
	ds_read_b128 v[240:243], v181 offset:480
	s_waitcnt lgkmcnt(5)
	v_mfma_f32_32x32x16_bf16 v[0:15], v[244:247], v[248:251], v[0:15]
	ds_read_b128 v[244:247], v220 offset:480
	s_waitcnt vmcnt(0) lgkmcnt(5)
	v_mfma_f32_32x32x16_bf16 v[112:127], v[224:227], v[212:215], v[112:127]
	ds_read_b128 v[224:227], v221 offset:480
	s_waitcnt lgkmcnt(5)
	v_mfma_f32_32x32x16_bf16 v[96:111], v[228:231], v[212:215], v[96:111]
	ds_read_b128 v[228:231], v222 offset:480
	s_waitcnt lgkmcnt(5)
	v_mfma_f32_32x32x16_bf16 v[80:95], v[232:235], v[212:215], v[80:95]
	s_waitcnt lgkmcnt(4)
	v_mfma_f32_32x32x16_bf16 v[64:79], v[236:239], v[212:215], v[64:79]
	s_waitcnt lgkmcnt(3)
	v_mfma_f32_32x32x16_bf16 v[48:63], v[240:243], v[212:215], v[48:63]
	s_waitcnt lgkmcnt(2)
	v_mfma_f32_32x32x16_bf16 v[32:47], v[244:247], v[212:215], v[32:47]
	s_waitcnt lgkmcnt(1)
	v_mfma_f32_32x32x16_bf16 v[16:31], v[224:227], v[212:215], v[16:31]
	s_waitcnt lgkmcnt(0)
	v_mfma_f32_32x32x16_bf16 v[0:15], v[228:231], v[212:215], v[0:15]
	s_movk_i32 s47, 0x200
	v_lshl_add_u64 v[244:245], v[160:161], 0, s[38:39]
	global_load_dwordx4 v[212:215], v[160:161], off offset:2432
	global_load_dwordx4 v[216:219], v[160:161], off offset:2304
	global_load_dwordx4 v[224:227], v[160:161], off offset:2176
	global_load_dwordx4 v[228:231], v[160:161], off offset:2048
	global_load_dwordx4 v[232:235], v[168:169], off offset:2048
	global_load_dwordx4 v[236:239], v[244:245], off offset:384
	global_load_dwordx4 v[240:243], v[244:245], off offset:256
	global_load_dwordx4 v[246:249], v[244:245], off offset:128
	v_mov_b32_e32 v170, v145
	v_mov_b32_e32 v171, v146
	v_mov_b32_e32 v145, v147
	v_mov_b32_e32 v146, v141
	v_mov_b32_e32 v147, v142
	v_mov_b32_e32 v141, v143
	v_pk_add_f32 v[144:145], v[170:171], v[144:145]
	v_pk_add_f32 v[140:141], v[146:147], v[140:141]
	v_pk_add_f32 v[144:145], v[144:145], v[144:145] op_sel:[0,1] op_sel_hi:[1,0]
	v_pk_add_f32 v[140:141], v[140:141], v[140:141] op_sel:[0,1] op_sel_hi:[1,0]
	v_add_f32_e32 v136, v136, v137
	v_add_f32_e32 v138, v138, v139
	v_mov_b32_e32 v145, v132
	v_mov_b32_e32 v141, v133
	v_mov_b32_e32 v137, v134
	v_mov_b32_e32 v139, v135
	v_pk_add_f32 v[132:133], v[144:145], v[140:141]
	v_pk_add_f32 v[134:135], v[136:137], v[138:139]
	s_lshl_b32 s10, s46, 1
	v_pk_add_f32 v[132:133], v[132:133], v[134:135]
	v_mov_b32_e32 v159, v149
	v_add_f32_e32 v132, v132, v133
	v_fmamk_f32 v132, v132, 0x3a800000, v180
	v_cmp_gt_f32_e32 vcc, s49, v132
	v_mul_f32_e32 v133, 0x4b800000, v132
	s_add_i32 s51, s51, 1
	v_cndmask_b32_e32 v132, v132, v133, vcc
	v_rsq_f32_e32 v132, v132
	s_nop 0
	v_mul_f32_e32 v133, 0x45800000, v132
	v_cndmask_b32_e32 v134, v132, v133, vcc
	v_mov_b32_e32 v132, v129
	v_mov_b32_e32 v133, v130
	v_mov_b32_e32 v129, v131
	v_pk_add_f32 v[128:129], v[132:133], v[128:129]
	v_and_b32_e32 v131, 64, v178
	v_add_f32_e32 v128, v128, v129
	v_mul_f32_e32 v129, v134, v134
	v_mul_f32_e32 v128, v128, v129
	v_fmamk_f32 v128, v128, 0x3b800000, v180
	v_cmp_gt_f32_e32 vcc, s49, v128
	v_mul_f32_e32 v129, 0x4b800000, v128
	v_add_u32_e32 v131, 64, v131
	v_cndmask_b32_e32 v128, v128, v129, vcc
	v_rsq_f32_e32 v128, v128
	s_nop 0
	v_mul_f32_e32 v129, 0x45800000, v128
	v_cndmask_b32_e32 v128, v128, v129, vcc
	v_max3_f32 v129, v112, s50, v113
	v_max3_f32 v129, v129, v114, v115
	v_max3_f32 v129, v129, v116, v117
	v_max3_f32 v129, v129, v118, v119
	v_max3_f32 v129, v129, v120, v121
	v_max3_f32 v129, v129, v122, v123
	v_max3_f32 v129, v129, v124, v125
	v_max3_f32 v129, v129, v126, v127
	v_max3_f32 v129, v129, v96, v97
	v_max3_f32 v129, v129, v98, v99
	v_max3_f32 v129, v129, v100, v101
	v_max3_f32 v129, v129, v102, v103
	v_max3_f32 v129, v129, v104, v105
	v_max3_f32 v129, v129, v106, v107
	v_max3_f32 v129, v129, v108, v109
	v_max3_f32 v129, v129, v110, v111
	v_max3_f32 v129, v129, v80, v81
	v_max3_f32 v129, v129, v82, v83
	v_max3_f32 v129, v129, v84, v85
	v_max3_f32 v129, v129, v86, v87
	v_max3_f32 v129, v129, v88, v89
	v_max3_f32 v129, v129, v90, v91
	v_max3_f32 v129, v129, v92, v93
	v_max3_f32 v129, v129, v94, v95
	v_max3_f32 v129, v129, v64, v65
	v_max3_f32 v129, v129, v66, v67
	v_max3_f32 v129, v129, v68, v69
	v_max3_f32 v129, v129, v70, v71
	v_max3_f32 v129, v129, v72, v73
	v_max3_f32 v129, v129, v74, v75
	v_max3_f32 v129, v129, v76, v77
	v_max3_f32 v129, v129, v78, v79
	v_max3_f32 v129, v129, v48, v49
	v_max3_f32 v129, v129, v50, v51
	v_max3_f32 v129, v129, v52, v53
	v_max3_f32 v129, v129, v54, v55
	v_max3_f32 v129, v129, v56, v57
	v_max3_f32 v129, v129, v58, v59
	v_max3_f32 v129, v129, v60, v61
	v_max3_f32 v129, v129, v62, v63
	v_max3_f32 v129, v129, v32, v33
	v_max3_f32 v129, v129, v34, v35
	v_max3_f32 v129, v129, v36, v37
	v_max3_f32 v129, v129, v38, v39
	v_max3_f32 v129, v129, v40, v41
	v_max3_f32 v129, v129, v42, v43
	v_max3_f32 v129, v129, v44, v45
	v_max3_f32 v129, v129, v46, v47
	v_max3_f32 v129, v129, v16, v17
	v_max3_f32 v129, v129, v18, v19
	v_max3_f32 v129, v129, v20, v21
	v_max3_f32 v129, v129, v22, v23
	v_max3_f32 v129, v129, v24, v25
	v_max3_f32 v129, v129, v26, v27
	v_max3_f32 v129, v129, v28, v29
	v_max3_f32 v129, v129, v30, v31
	v_max3_f32 v129, v129, v0, v1
	v_max3_f32 v129, v129, v2, v3
	v_max3_f32 v129, v129, v4, v5
	v_max3_f32 v129, v129, v6, v7
	v_max3_f32 v129, v129, v8, v9
	v_max3_f32 v129, v129, v10, v11
	v_mul_f32_e32 v128, v134, v128
	v_max3_f32 v129, v129, v12, v13
	v_max3_f32 v130, v129, v14, v15
	v_mul_f32_e32 v129, 0x3db8aa3b, v128
	v_xor_b32_e32 v128, 32, v178
	v_cmp_lt_i32_e32 vcc, v128, v131
	v_mul_f32_e32 v130, v129, v130
	s_nop 0
	v_cndmask_b32_e32 v128, v178, v128, vcc
	v_lshlrev_b32_e32 v128, 2, v128
	ds_bpermute_b32 v131, v128, v130
	s_waitcnt lgkmcnt(0)
	v_max_f32_e32 v131, v131, v131
	v_max_f32_e32 v130, v130, v131
	v_fma_f32 v112, v129, v112, -v130
	v_exp_f32_e32 v112, v112
	v_fma_f32 v113, v129, v113, -v130
	v_exp_f32_e32 v113, v113
	v_fma_f32 v114, v129, v114, -v130
	v_exp_f32_e32 v114, v114
	v_fma_f32 v115, v129, v115, -v130
	v_exp_f32_e32 v115, v115
	v_fma_f32 v116, v129, v116, -v130
	v_add_f32_e32 v131, 0, v112
	v_exp_f32_e32 v132, v116
	v_add_f32_e32 v131, v113, v131
	v_add_f32_e32 v131, v114, v131
	v_add_f32_e32 v131, v115, v131
	v_fma_f32 v117, v129, v117, -v130
	v_add_f32_e32 v116, v132, v131
	v_exp_f32_e32 v131, v117
	v_fma_f32 v117, v129, v118, -v130
	v_exp_f32_e32 v133, v117
	v_fma_f32 v117, v129, v119, -v130
	v_exp_f32_e32 v119, v117
	v_fma_f32 v117, v129, v120, -v130
	v_exp_f32_e32 v120, v117
	v_fma_f32 v117, v129, v121, -v130
	v_add_f32_e32 v116, v131, v116
	v_exp_f32_e32 v121, v117
	v_fma_f32 v117, v129, v122, -v130
	v_add_f32_e32 v116, v133, v116
	v_exp_f32_e32 v122, v117
	v_fma_f32 v117, v129, v123, -v130
	v_add_f32_e32 v116, v119, v116
	v_exp_f32_e32 v123, v117
	v_fma_f32 v117, v129, v124, -v130
	v_add_f32_e32 v116, v120, v116
	v_exp_f32_e32 v124, v117
	v_fma_f32 v117, v129, v125, -v130
	v_add_f32_e32 v116, v121, v116
	v_exp_f32_e32 v125, v117
	v_fma_f32 v117, v129, v126, -v130
	v_add_f32_e32 v116, v122, v116
	v_exp_f32_e32 v126, v117
	v_fma_f32 v117, v129, v127, -v130
	v_add_f32_e32 v116, v123, v116
	v_exp_f32_e32 v127, v117
	v_fma_f32 v96, v129, v96, -v130
	v_add_f32_e32 v116, v124, v116
	v_exp_f32_e32 v96, v96
	v_fma_f32 v97, v129, v97, -v130
	v_add_f32_e32 v116, v125, v116
	v_exp_f32_e32 v97, v97
	v_fma_f32 v98, v129, v98, -v130
	v_add_f32_e32 v116, v126, v116
	v_exp_f32_e32 v98, v98
	v_fma_f32 v99, v129, v99, -v130
	v_add_f32_e32 v134, v127, v116
	v_exp_f32_e32 v99, v99
	v_fma_f32 v100, v129, v100, -v130
	v_cvt_pk_bf16_f32 v116, v112, v113
	v_cvt_pk_bf16_f32 v112, v120, v121
	v_add_f32_e32 v120, v96, v134
	v_exp_f32_e32 v121, v100
	v_add_f32_e32 v120, v97, v120
	v_add_f32_e32 v120, v98, v120
	v_add_f32_e32 v120, v99, v120
	v_fma_f32 v101, v129, v101, -v130
	v_add_f32_e32 v100, v121, v120
	v_exp_f32_e32 v120, v101
	v_fma_f32 v101, v129, v102, -v130
	v_cvt_pk_bf16_f32 v113, v122, v123
	v_exp_f32_e32 v122, v101
	v_fma_f32 v101, v129, v103, -v130
	v_exp_f32_e32 v103, v101
	v_fma_f32 v101, v129, v104, -v130
	v_exp_f32_e32 v104, v101
	v_fma_f32 v101, v129, v105, -v130
	v_add_f32_e32 v100, v120, v100
	v_exp_f32_e32 v105, v101
	v_fma_f32 v101, v129, v106, -v130
	v_add_f32_e32 v100, v122, v100
	v_exp_f32_e32 v106, v101
	v_fma_f32 v101, v129, v107, -v130
	v_add_f32_e32 v100, v103, v100
	v_exp_f32_e32 v107, v101
	v_fma_f32 v101, v129, v108, -v130
	v_add_f32_e32 v100, v104, v100
	v_exp_f32_e32 v108, v101
	v_fma_f32 v101, v129, v109, -v130
	v_add_f32_e32 v100, v105, v100
	v_exp_f32_e32 v109, v101
	v_fma_f32 v101, v129, v110, -v130
	v_add_f32_e32 v100, v106, v100
	v_exp_f32_e32 v110, v101
	v_fma_f32 v101, v129, v111, -v130
	v_add_f32_e32 v100, v107, v100
	v_exp_f32_e32 v111, v101
	v_fma_f32 v80, v129, v80, -v130
	v_add_f32_e32 v100, v108, v100
	v_exp_f32_e32 v80, v80
	v_fma_f32 v81, v129, v81, -v130
	v_add_f32_e32 v100, v109, v100
	v_exp_f32_e32 v81, v81
	v_fma_f32 v82, v129, v82, -v130
	v_add_f32_e32 v100, v110, v100
	v_exp_f32_e32 v82, v82
	v_fma_f32 v83, v129, v83, -v130
	v_add_f32_e32 v123, v111, v100
	v_exp_f32_e32 v83, v83
	v_fma_f32 v84, v129, v84, -v130
	v_cvt_pk_bf16_f32 v100, v96, v97
	v_cvt_pk_bf16_f32 v96, v104, v105
	v_add_f32_e32 v104, v80, v123
	v_exp_f32_e32 v105, v84
	v_add_f32_e32 v104, v81, v104
	v_add_f32_e32 v104, v82, v104
	v_add_f32_e32 v104, v83, v104
	v_fma_f32 v85, v129, v85, -v130
	v_add_f32_e32 v84, v105, v104
	v_exp_f32_e32 v104, v85
	v_fma_f32 v85, v129, v86, -v130
	v_cvt_pk_bf16_f32 v97, v106, v107
	v_exp_f32_e32 v106, v85
	v_fma_f32 v85, v129, v87, -v130
	v_exp_f32_e32 v87, v85
	v_fma_f32 v85, v129, v88, -v130
	v_exp_f32_e32 v88, v85
	v_fma_f32 v85, v129, v89, -v130
	v_add_f32_e32 v84, v104, v84
	v_exp_f32_e32 v89, v85
	v_fma_f32 v85, v129, v90, -v130
	v_add_f32_e32 v84, v106, v84
	v_exp_f32_e32 v90, v85
	v_fma_f32 v85, v129, v91, -v130
	v_add_f32_e32 v84, v87, v84
	v_exp_f32_e32 v91, v85
	v_fma_f32 v85, v129, v92, -v130
	v_add_f32_e32 v84, v88, v84
	v_exp_f32_e32 v92, v85
	v_fma_f32 v85, v129, v93, -v130
	v_add_f32_e32 v84, v89, v84
	v_exp_f32_e32 v93, v85
	v_fma_f32 v85, v129, v94, -v130
	v_add_f32_e32 v84, v90, v84
	v_exp_f32_e32 v94, v85
	v_fma_f32 v85, v129, v95, -v130
	v_add_f32_e32 v84, v91, v84
	v_exp_f32_e32 v95, v85
	v_fma_f32 v64, v129, v64, -v130
	v_add_f32_e32 v84, v92, v84
	v_exp_f32_e32 v64, v64
	v_fma_f32 v65, v129, v65, -v130
	v_add_f32_e32 v84, v93, v84
	v_exp_f32_e32 v65, v65
	v_fma_f32 v66, v129, v66, -v130
	v_add_f32_e32 v84, v94, v84
	v_exp_f32_e32 v66, v66
	v_fma_f32 v67, v129, v67, -v130
	v_add_f32_e32 v107, v95, v84
	v_exp_f32_e32 v67, v67
	v_fma_f32 v68, v129, v68, -v130
	v_cvt_pk_bf16_f32 v84, v80, v81
	v_cvt_pk_bf16_f32 v80, v88, v89
	v_add_f32_e32 v88, v64, v107
	v_exp_f32_e32 v89, v68
	v_add_f32_e32 v88, v65, v88
	v_add_f32_e32 v88, v66, v88
	v_add_f32_e32 v88, v67, v88
	v_fma_f32 v69, v129, v69, -v130
	v_add_f32_e32 v68, v89, v88
	v_exp_f32_e32 v88, v69
	v_fma_f32 v69, v129, v70, -v130
	v_cvt_pk_bf16_f32 v81, v90, v91
	v_exp_f32_e32 v90, v69
	v_fma_f32 v69, v129, v71, -v130
	v_exp_f32_e32 v71, v69
	v_fma_f32 v69, v129, v72, -v130
	v_exp_f32_e32 v72, v69
	v_fma_f32 v69, v129, v73, -v130
	v_add_f32_e32 v68, v88, v68
	v_exp_f32_e32 v73, v69
	v_fma_f32 v69, v129, v74, -v130
	v_add_f32_e32 v68, v90, v68
	v_exp_f32_e32 v74, v69
	v_fma_f32 v69, v129, v75, -v130
	v_add_f32_e32 v68, v71, v68
	v_exp_f32_e32 v75, v69
	v_fma_f32 v69, v129, v76, -v130
	v_add_f32_e32 v68, v72, v68
	v_exp_f32_e32 v76, v69
	v_fma_f32 v69, v129, v77, -v130
	v_add_f32_e32 v68, v73, v68
	v_exp_f32_e32 v77, v69
	v_fma_f32 v69, v129, v78, -v130
	v_add_f32_e32 v68, v74, v68
	v_exp_f32_e32 v78, v69
	v_fma_f32 v69, v129, v79, -v130
	v_add_f32_e32 v68, v75, v68
	v_exp_f32_e32 v79, v69
	v_fma_f32 v48, v129, v48, -v130
	v_add_f32_e32 v68, v76, v68
	v_exp_f32_e32 v48, v48
	v_fma_f32 v49, v129, v49, -v130
	v_add_f32_e32 v68, v77, v68
	v_exp_f32_e32 v49, v49
	v_fma_f32 v50, v129, v50, -v130
	v_add_f32_e32 v68, v78, v68
	v_exp_f32_e32 v50, v50
	v_fma_f32 v51, v129, v51, -v130
	v_add_f32_e32 v91, v79, v68
	v_exp_f32_e32 v51, v51
	v_fma_f32 v52, v129, v52, -v130
	v_cvt_pk_bf16_f32 v68, v64, v65
	v_cvt_pk_bf16_f32 v64, v72, v73
	v_add_f32_e32 v72, v48, v91
	v_exp_f32_e32 v73, v52
	v_add_f32_e32 v72, v49, v72
	v_add_f32_e32 v72, v50, v72
	v_add_f32_e32 v72, v51, v72
	v_fma_f32 v53, v129, v53, -v130
	v_add_f32_e32 v52, v73, v72
	v_exp_f32_e32 v72, v53
	v_fma_f32 v53, v129, v54, -v130
	v_cvt_pk_bf16_f32 v65, v74, v75
	v_exp_f32_e32 v74, v53
	v_fma_f32 v53, v129, v55, -v130
	v_exp_f32_e32 v55, v53
	v_fma_f32 v53, v129, v56, -v130
	v_exp_f32_e32 v56, v53
	v_fma_f32 v53, v129, v57, -v130
	v_add_f32_e32 v52, v72, v52
	v_exp_f32_e32 v57, v53
	v_fma_f32 v53, v129, v58, -v130
	v_add_f32_e32 v52, v74, v52
	v_exp_f32_e32 v58, v53
	v_fma_f32 v53, v129, v59, -v130
	v_add_f32_e32 v52, v55, v52
	v_exp_f32_e32 v59, v53
	v_fma_f32 v53, v129, v60, -v130
	v_add_f32_e32 v52, v56, v52
	v_exp_f32_e32 v60, v53
	v_fma_f32 v53, v129, v61, -v130
	v_add_f32_e32 v52, v57, v52
	v_exp_f32_e32 v61, v53
	v_fma_f32 v53, v129, v62, -v130
	v_add_f32_e32 v52, v58, v52
	v_exp_f32_e32 v62, v53
	v_fma_f32 v53, v129, v63, -v130
	v_add_f32_e32 v52, v59, v52
	v_exp_f32_e32 v63, v53
	v_fma_f32 v32, v129, v32, -v130
	v_add_f32_e32 v52, v60, v52
	v_exp_f32_e32 v32, v32
	v_fma_f32 v33, v129, v33, -v130
	v_add_f32_e32 v52, v61, v52
	v_exp_f32_e32 v33, v33
	v_fma_f32 v34, v129, v34, -v130
	v_add_f32_e32 v52, v62, v52
	v_exp_f32_e32 v34, v34
	v_fma_f32 v35, v129, v35, -v130
	v_add_f32_e32 v75, v63, v52
	v_exp_f32_e32 v35, v35
	v_fma_f32 v36, v129, v36, -v130
	v_cvt_pk_bf16_f32 v52, v48, v49
	v_cvt_pk_bf16_f32 v48, v56, v57
	v_add_f32_e32 v56, v32, v75
	v_exp_f32_e32 v57, v36
	v_add_f32_e32 v56, v33, v56
	v_add_f32_e32 v56, v34, v56
	v_add_f32_e32 v56, v35, v56
	v_fma_f32 v37, v129, v37, -v130
	v_add_f32_e32 v36, v57, v56
	v_exp_f32_e32 v56, v37
	v_fma_f32 v37, v129, v38, -v130
	v_cvt_pk_bf16_f32 v49, v58, v59
	v_exp_f32_e32 v58, v37
	v_fma_f32 v37, v129, v39, -v130
	v_exp_f32_e32 v39, v37
	v_fma_f32 v37, v129, v40, -v130
	v_exp_f32_e32 v40, v37
	v_fma_f32 v37, v129, v41, -v130
	v_add_f32_e32 v36, v56, v36
	v_exp_f32_e32 v41, v37
	v_fma_f32 v37, v129, v42, -v130
	v_add_f32_e32 v36, v58, v36
	v_exp_f32_e32 v42, v37
	v_fma_f32 v37, v129, v43, -v130
	v_add_f32_e32 v36, v39, v36
	v_exp_f32_e32 v43, v37
	v_fma_f32 v37, v129, v44, -v130
	v_add_f32_e32 v36, v40, v36
	v_exp_f32_e32 v44, v37
	v_fma_f32 v37, v129, v45, -v130
	v_add_f32_e32 v36, v41, v36
	v_exp_f32_e32 v45, v37
	v_fma_f32 v37, v129, v46, -v130
	v_add_f32_e32 v36, v42, v36
	v_exp_f32_e32 v46, v37
	v_fma_f32 v37, v129, v47, -v130
	v_add_f32_e32 v36, v43, v36
	v_exp_f32_e32 v47, v37
	v_fma_f32 v16, v129, v16, -v130
	v_add_f32_e32 v36, v44, v36
	v_exp_f32_e32 v16, v16
	v_fma_f32 v17, v129, v17, -v130
	v_add_f32_e32 v36, v45, v36
	v_exp_f32_e32 v17, v17
	v_fma_f32 v18, v129, v18, -v130
	v_add_f32_e32 v36, v46, v36
	v_exp_f32_e32 v18, v18
	v_fma_f32 v19, v129, v19, -v130
	v_add_f32_e32 v59, v47, v36
	v_exp_f32_e32 v19, v19
	v_fma_f32 v20, v129, v20, -v130
	v_cvt_pk_bf16_f32 v36, v32, v33
	v_cvt_pk_bf16_f32 v32, v40, v41
	v_add_f32_e32 v40, v16, v59
	v_exp_f32_e32 v41, v20
	v_add_f32_e32 v40, v17, v40
	v_add_f32_e32 v40, v18, v40
	v_add_f32_e32 v40, v19, v40
	v_fma_f32 v21, v129, v21, -v130
	v_add_f32_e32 v20, v41, v40
	v_exp_f32_e32 v40, v21
	v_fma_f32 v21, v129, v22, -v130
	v_cvt_pk_bf16_f32 v33, v42, v43
	v_exp_f32_e32 v42, v21
	v_fma_f32 v21, v129, v23, -v130
	v_exp_f32_e32 v23, v21
	v_fma_f32 v21, v129, v24, -v130
	v_exp_f32_e32 v24, v21
	v_fma_f32 v21, v129, v25, -v130
	v_add_f32_e32 v20, v40, v20
	v_exp_f32_e32 v25, v21
	v_fma_f32 v21, v129, v26, -v130
	v_add_f32_e32 v20, v42, v20
	v_exp_f32_e32 v26, v21
	v_fma_f32 v21, v129, v27, -v130
	v_add_f32_e32 v20, v23, v20
	v_exp_f32_e32 v27, v21
	v_fma_f32 v21, v129, v28, -v130
	v_add_f32_e32 v20, v24, v20
	v_exp_f32_e32 v28, v21
	v_fma_f32 v21, v129, v29, -v130
	v_add_f32_e32 v20, v25, v20
	v_exp_f32_e32 v29, v21
	v_fma_f32 v21, v129, v30, -v130
	v_add_f32_e32 v20, v26, v20
	v_exp_f32_e32 v30, v21
	v_fma_f32 v21, v129, v31, -v130
	v_add_f32_e32 v20, v27, v20
	v_exp_f32_e32 v31, v21
	v_fma_f32 v0, v129, v0, -v130
	v_add_f32_e32 v20, v28, v20
	v_exp_f32_e32 v0, v0
	v_fma_f32 v1, v129, v1, -v130
	v_add_f32_e32 v20, v29, v20
	v_exp_f32_e32 v1, v1
	v_fma_f32 v2, v129, v2, -v130
	v_add_f32_e32 v20, v30, v20
	v_exp_f32_e32 v2, v2
	v_fma_f32 v3, v129, v3, -v130
	v_add_f32_e32 v43, v31, v20
	v_exp_f32_e32 v3, v3
	v_fma_f32 v4, v129, v4, -v130
	v_cvt_pk_bf16_f32 v20, v16, v17
	v_cvt_pk_bf16_f32 v16, v24, v25
	v_add_f32_e32 v24, v0, v43
	v_exp_f32_e32 v4, v4
	v_fma_f32 v5, v129, v5, -v130
	v_add_f32_e32 v24, v1, v24
	v_exp_f32_e32 v5, v5
	v_fma_f32 v6, v129, v6, -v130
	v_add_f32_e32 v24, v2, v24
	v_exp_f32_e32 v6, v6
	v_fma_f32 v7, v129, v7, -v130
	v_add_f32_e32 v24, v3, v24
	v_exp_f32_e32 v7, v7
	v_fma_f32 v8, v129, v8, -v130
	v_add_f32_e32 v24, v4, v24
	v_exp_f32_e32 v8, v8
	v_fma_f32 v9, v129, v9, -v130
	v_add_f32_e32 v24, v5, v24
	v_exp_f32_e32 v9, v9
	v_fma_f32 v10, v129, v10, -v130
	v_add_f32_e32 v24, v6, v24
	v_exp_f32_e32 v10, v10
	v_fma_f32 v11, v129, v11, -v130
	v_add_f32_e32 v24, v7, v24
	v_exp_f32_e32 v11, v11
	v_fma_f32 v12, v129, v12, -v130
	v_add_f32_e32 v24, v8, v24
	v_exp_f32_e32 v12, v12
	v_fma_f32 v13, v129, v13, -v130
	v_add_f32_e32 v24, v9, v24
	v_exp_f32_e32 v13, v13
	v_fma_f32 v14, v129, v14, -v130
	v_add_f32_e32 v24, v10, v24
	v_exp_f32_e32 v14, v14
	v_fma_f32 v15, v129, v15, -v130
	v_add_f32_e32 v24, v11, v24
	v_exp_f32_e32 v15, v15
	v_add_f32_e32 v24, v12, v24
	v_add_f32_e32 v24, v13, v24
	v_add_f32_e32 v24, v14, v24
	v_cvt_pk_bf16_f32 v22, v41, v40
	v_add_f32_e32 v40, v15, v24
	v_cvt_pk_bf16_f32 v21, v18, v19
	v_cvt_pk_bf16_f32 v18, v28, v29
	v_cvt_pk_bf16_f32 v28, v0, v1
	ds_bpermute_b32 v0, v128, v40
	v_cvt_pk_bf16_f32 v117, v114, v115
	v_cvt_pk_bf16_f32 v118, v132, v131
	v_cvt_pk_bf16_f32 v119, v133, v119
	v_cvt_pk_bf16_f32 v114, v124, v125
	v_cvt_pk_bf16_f32 v115, v126, v127
	v_cvt_pk_bf16_f32 v101, v98, v99
	v_cvt_pk_bf16_f32 v102, v121, v120
	v_cvt_pk_bf16_f32 v103, v122, v103
	v_cvt_pk_bf16_f32 v98, v108, v109
	v_cvt_pk_bf16_f32 v99, v110, v111
	v_cvt_pk_bf16_f32 v85, v82, v83
	v_cvt_pk_bf16_f32 v86, v105, v104
	v_cvt_pk_bf16_f32 v87, v106, v87
	v_cvt_pk_bf16_f32 v82, v92, v93
	v_cvt_pk_bf16_f32 v83, v94, v95
	v_cvt_pk_bf16_f32 v69, v66, v67
	v_cvt_pk_bf16_f32 v70, v89, v88
	v_cvt_pk_bf16_f32 v71, v90, v71
	v_cvt_pk_bf16_f32 v66, v76, v77
	v_cvt_pk_bf16_f32 v67, v78, v79
	v_cvt_pk_bf16_f32 v53, v50, v51
	v_cvt_pk_bf16_f32 v54, v73, v72
	v_cvt_pk_bf16_f32 v55, v74, v55
	v_cvt_pk_bf16_f32 v50, v60, v61
	v_cvt_pk_bf16_f32 v51, v62, v63
	v_cvt_pk_bf16_f32 v37, v34, v35
	v_cvt_pk_bf16_f32 v38, v57, v56
	v_cvt_pk_bf16_f32 v39, v58, v39
	v_cvt_pk_bf16_f32 v34, v44, v45
	v_cvt_pk_bf16_f32 v35, v46, v47
	v_cvt_pk_bf16_f32 v23, v42, v23
	v_cvt_pk_bf16_f32 v17, v26, v27
	v_cvt_pk_bf16_f32 v19, v30, v31
	v_cvt_pk_bf16_f32 v29, v2, v3
	v_cvt_pk_bf16_f32 v30, v4, v5
	v_cvt_pk_bf16_f32 v31, v6, v7
	v_cvt_pk_bf16_f32 v24, v8, v9
	v_cvt_pk_bf16_f32 v25, v10, v11
	v_cvt_pk_bf16_f32 v26, v12, v13
	v_cvt_pk_bf16_f32 v27, v14, v15
	v_lshl_add_u64 v[60:61], v[160:161], 0, s[38:39]
	s_waitcnt lgkmcnt(0)
	v_add_f32_e32 v72, v40, v0
	s_barrier
	s_waitcnt vmcnt(0)
	ds_write_b128 v172, v[228:231]
	ds_write_b128 v172, v[224:227] offset:128
	ds_write_b128 v172, v[216:219] offset:256
	ds_write_b128 v172, v[212:215] offset:384
	ds_write_b128 v172, v[232:235] offset:35840
	ds_write_b128 v172, v[246:249] offset:35968
	ds_write_b128 v172, v[240:243] offset:36096
	ds_write_b128 v172, v[236:239] offset:36224
	v_lshl_add_u64 v[12:13], v[160:161], 0, s[40:41]
	v_lshl_add_u64 v[60:61], v[160:161], 0, s[44:45]
	global_load_dwordx4 v[0:3], v[164:165], off offset:2048
	global_load_dwordx4 v[4:7], v[12:13], off offset:384
	global_load_dwordx4 v[8:11], v[12:13], off offset:256
	s_nop 0
	global_load_dwordx4 v[12:15], v[12:13], off offset:128
	s_nop 0
	global_load_dwordx4 v[40:43], v[166:167], off offset:2048
	global_load_dwordx4 v[44:47], v[60:61], off offset:384
	global_load_dwordx4 v[56:59], v[60:61], off offset:256
	s_nop 0
	global_load_dwordx4 v[60:63], v[60:61], off offset:128
	s_waitcnt vmcnt(7)
	ds_write_b128 v173, v[0:3]
	s_waitcnt vmcnt(4)
	ds_write_b128 v174, v[12:15]
	ds_write_b128 v175, v[8:11]
	ds_write_b128 v179, v[4:7]
	s_waitcnt vmcnt(3)
	ds_write_b128 v182, v[40:43]
	s_waitcnt vmcnt(0)
	ds_write_b128 v183, v[60:63]
	ds_write_b128 v184, v[56:59]
	ds_write_b128 v185, v[44:47]
	v_div_scale_f32 v0, s[4:5], v72, v72, 1.0
	v_rcp_f32_e32 v1, v0
	s_waitcnt lgkmcnt(0)
	s_barrier
	v_fma_f32 v2, -v0, v1, 1.0
	v_fmac_f32_e32 v1, v2, v1
	v_div_scale_f32 v2, vcc, 1.0, v72, 1.0
	v_mul_f32_e32 v3, v2, v1
	v_fma_f32 v4, -v0, v3, v2
	v_fmac_f32_e32 v3, v4, v1
	v_fma_f32 v0, -v0, v3, v2
	v_div_fmas_f32 v0, v0, v1, v3
	v_div_fixup_f32 v44, v0, v72, 1.0
	v_lshl_add_u64 v[0:1], s[12:13], 0, v[162:163]
	v_lshl_add_u64 v[0:1], v[0:1], 0, s[10:11]
	v_lshl_add_u64 v[46:47], v[0:1], 0, v[158:159]
	v_mbcnt_lo_u32_b32 v40, -1, 0
	v_mbcnt_hi_u32_b32 v40, -1, v40
	v_and_b32_e32 v40, 32, v40
	v_lshrrev_b32_e32 v40, 2, v40
	v_mov_b32_e32 v41, 0
	v_lshl_add_u64 v[124:125], v[46:47], 0, v[40:41]
	ds_read_b64_tr_b16 v[56:57], v186
	ds_read_b64_tr_b16 v[58:59], v186 offset:4480
	ds_read_b64_tr_b16 v[60:61], v186 offset:8960
	ds_read_b64_tr_b16 v[62:63], v186 offset:13440
	ds_read_b64_tr_b16 v[88:89], v186 offset:17920
	ds_read_b64_tr_b16 v[90:91], v186 offset:22400
	ds_read_b64_tr_b16 v[92:93], v186 offset:26880
	ds_read_b64_tr_b16 v[94:95], v186 offset:31360
	ds_read_b64_tr_b16 v[104:105], v186 offset:35840
	ds_read_b64_tr_b16 v[106:107], v186 offset:40320
	ds_read_b64_tr_b16 v[108:109], v186 offset:44800
	ds_read_b64_tr_b16 v[110:111], v186 offset:49280
	ds_read_b64_tr_b16 v[120:121], v186 offset:53760
	ds_read_b64_tr_b16 v[122:123], v186 offset:58240
	s_mov_b64 s[4:5], 0
	s_waitcnt lgkmcnt(12)
	v_mfma_f32_32x32x16_bf16 v[0:15], v[56:59], v[116:119], 0
	v_add_u32_e32 v40, v187, v177
	ds_read_b64_tr_b16 v[56:57], v186 offset:62720
	ds_read_b64_tr_b16 v[58:59], v40
	s_waitcnt lgkmcnt(12)
	v_mfma_f32_32x32x16_bf16 v[0:15], v[60:63], v[112:115], v[0:15]
	v_add_u32_e32 v40, v188, v177
	v_add_u32_e32 v42, v189, v177
	ds_read_b64_tr_b16 v[60:61], v40
	ds_read_b64_tr_b16 v[62:63], v42
	s_waitcnt lgkmcnt(12)
	v_mfma_f32_32x32x16_bf16 v[0:15], v[88:91], v[100:103], v[0:15]
	v_add_u32_e32 v40, v190, v177
	v_add_u32_e32 v42, v191, v177
	ds_read_b64_tr_b16 v[88:89], v40
	ds_read_b64_tr_b16 v[90:91], v42
	s_waitcnt lgkmcnt(12)
	v_mfma_f32_32x32x16_bf16 v[0:15], v[92:95], v[96:99], v[0:15]
	v_add_u32_e32 v40, v192, v177
	v_add_u32_e32 v42, v193, v177
	ds_read_b64_tr_b16 v[92:93], v40
	ds_read_b64_tr_b16 v[94:95], v42
	s_waitcnt lgkmcnt(12)
	v_mfma_f32_32x32x16_bf16 v[0:15], v[104:107], v[84:87], v[0:15]
	v_add_u32_e32 v40, v194, v177
	v_add_u32_e32 v42, v195, v177
	ds_read_b64_tr_b16 v[104:105], v40
	ds_read_b64_tr_b16 v[106:107], v42
	s_waitcnt lgkmcnt(12)
	v_mfma_f32_32x32x16_bf16 v[0:15], v[108:111], v[80:83], v[0:15]
	v_add_u32_e32 v40, v196, v177
	v_add_u32_e32 v42, v197, v177
	ds_read_b64_tr_b16 v[108:109], v40
	ds_read_b64_tr_b16 v[110:111], v42
	s_waitcnt lgkmcnt(12)
	v_mfma_f32_32x32x16_bf16 v[0:15], v[120:123], v[68:71], v[0:15]
	v_add_u32_e32 v40, v198, v177
	v_add_u32_e32 v42, v199, v177
	ds_read_b64_tr_b16 v[120:121], v40
	ds_read_b64_tr_b16 v[122:123], v42
	s_waitcnt lgkmcnt(12)
	v_mfma_f32_32x32x16_bf16 v[0:15], v[56:59], v[64:67], v[0:15]
	v_add_u32_e32 v40, v200, v177
	v_add_u32_e32 v42, v201, v177
	ds_read_b64_tr_b16 v[56:57], v40
	ds_read_b64_tr_b16 v[58:59], v42
	s_waitcnt lgkmcnt(12)
	v_mfma_f32_32x32x16_bf16 v[0:15], v[60:63], v[52:55], v[0:15]
	v_add_u32_e32 v40, v202, v177
	v_add_u32_e32 v42, v203, v177
	ds_read_b64_tr_b16 v[60:61], v40
	ds_read_b64_tr_b16 v[62:63], v42
	s_waitcnt lgkmcnt(12)
	v_mfma_f32_32x32x16_bf16 v[0:15], v[88:91], v[48:51], v[0:15]
	ds_read_b64_tr_b16 v[88:89], v186 offset:64
	ds_read_b64_tr_b16 v[90:91], v186 offset:4544
	s_waitcnt lgkmcnt(12)
	v_mfma_f32_32x32x16_bf16 v[0:15], v[92:95], v[36:39], v[0:15]
	ds_read_b64_tr_b16 v[92:93], v186 offset:9024
	ds_read_b64_tr_b16 v[94:95], v186 offset:13504
	s_waitcnt lgkmcnt(12)
	v_mfma_f32_32x32x16_bf16 v[0:15], v[104:107], v[32:35], v[0:15]
	ds_read_b64_tr_b16 v[104:105], v186 offset:17984
	ds_read_b64_tr_b16 v[106:107], v186 offset:22464
	s_waitcnt lgkmcnt(12)
	v_mfma_f32_32x32x16_bf16 v[0:15], v[108:111], v[20:23], v[0:15]
	ds_read_b64_tr_b16 v[108:109], v186 offset:26944
	ds_read_b64_tr_b16 v[110:111], v186 offset:31424
	s_waitcnt lgkmcnt(12)
	v_mfma_f32_32x32x16_bf16 v[0:15], v[120:123], v[16:19], v[0:15]
	ds_read_b64_tr_b16 v[120:121], v186 offset:35904
	ds_read_b64_tr_b16 v[122:123], v186 offset:40384
	s_waitcnt lgkmcnt(12)
	v_mfma_f32_32x32x16_bf16 v[0:15], v[56:59], v[28:31], v[0:15]
	ds_read_b64_tr_b16 v[56:57], v186 offset:44864
	ds_read_b64_tr_b16 v[58:59], v186 offset:49344
	s_waitcnt lgkmcnt(12)
	v_mfma_f32_32x32x16_bf16 v[0:15], v[60:63], v[24:27], v[0:15]
	ds_read_b64_tr_b16 v[60:61], v186 offset:53824
	ds_read_b64_tr_b16 v[62:63], v186 offset:58304
	s_nop 11
	v_pk_mul_f32 v[0:1], v[0:1], v[44:45] op_sel_hi:[1,0]
	v_pk_mul_f32 v[2:3], v[2:3], v[44:45] op_sel_hi:[1,0]
	v_pk_mul_f32 v[4:5], v[4:5], v[44:45] op_sel_hi:[1,0]
	v_pk_mul_f32 v[6:7], v[6:7], v[44:45] op_sel_hi:[1,0]
	v_cvt_pk_bf16_f32 v0, v0, v1
	v_cvt_pk_bf16_f32 v1, v2, v3
	v_cvt_pk_bf16_f32 v2, v4, v5
	v_cvt_pk_bf16_f32 v3, v6, v7
	s_nop 1
	v_permlane32_swap_b32_e32 v0, v2
	v_permlane32_swap_b32_e32 v1, v3
	global_store_dwordx4 v[124:125], v[0:3], off
	v_pk_mul_f32 v[8:9], v[8:9], v[44:45] op_sel_hi:[1,0]
	v_pk_mul_f32 v[10:11], v[10:11], v[44:45] op_sel_hi:[1,0]
	v_pk_mul_f32 v[12:13], v[12:13], v[44:45] op_sel_hi:[1,0]
	v_pk_mul_f32 v[14:15], v[14:15], v[44:45] op_sel_hi:[1,0]
	v_cvt_pk_bf16_f32 v4, v8, v9
	v_cvt_pk_bf16_f32 v5, v10, v11
	v_cvt_pk_bf16_f32 v6, v12, v13
	v_cvt_pk_bf16_f32 v7, v14, v15
	s_nop 1
	v_permlane32_swap_b32_e32 v4, v6
	v_permlane32_swap_b32_e32 v5, v7
	global_store_dwordx4 v[124:125], v[4:7], off offset:32
	s_nop 1
	s_waitcnt lgkmcnt(12)
	v_mfma_f32_32x32x16_bf16 v[0:15], v[88:91], v[116:119], 0
	v_add_u32_e32 v40, v187, v204
	ds_read_b64_tr_b16 v[88:89], v186 offset:62784
	ds_read_b64_tr_b16 v[90:91], v40
	s_waitcnt lgkmcnt(12)
	v_mfma_f32_32x32x16_bf16 v[0:15], v[92:95], v[112:115], v[0:15]
	v_add_u32_e32 v40, v188, v204
	v_add_u32_e32 v42, v189, v204
	ds_read_b64_tr_b16 v[92:93], v40
	ds_read_b64_tr_b16 v[94:95], v42
	s_waitcnt lgkmcnt(12)
	v_mfma_f32_32x32x16_bf16 v[0:15], v[104:107], v[100:103], v[0:15]
	v_add_u32_e32 v40, v190, v204
	v_add_u32_e32 v42, v191, v204
	ds_read_b64_tr_b16 v[104:105], v40
	ds_read_b64_tr_b16 v[106:107], v42
	s_waitcnt lgkmcnt(12)
	v_mfma_f32_32x32x16_bf16 v[0:15], v[108:111], v[96:99], v[0:15]
	v_add_u32_e32 v40, v192, v204
	v_add_u32_e32 v42, v193, v204
	ds_read_b64_tr_b16 v[108:109], v40
	ds_read_b64_tr_b16 v[110:111], v42
	s_waitcnt lgkmcnt(12)
	v_mfma_f32_32x32x16_bf16 v[0:15], v[120:123], v[84:87], v[0:15]
	v_add_u32_e32 v40, v194, v204
	v_add_u32_e32 v42, v195, v204
	ds_read_b64_tr_b16 v[120:121], v40
	ds_read_b64_tr_b16 v[122:123], v42
	s_waitcnt lgkmcnt(12)
	v_mfma_f32_32x32x16_bf16 v[0:15], v[56:59], v[80:83], v[0:15]
	v_add_u32_e32 v40, v196, v204
	v_add_u32_e32 v42, v197, v204
	ds_read_b64_tr_b16 v[56:57], v40
	ds_read_b64_tr_b16 v[58:59], v42
	s_waitcnt lgkmcnt(12)
	v_mfma_f32_32x32x16_bf16 v[0:15], v[60:63], v[68:71], v[0:15]
	v_add_u32_e32 v40, v198, v204
	v_add_u32_e32 v42, v199, v204
	ds_read_b64_tr_b16 v[60:61], v40
	ds_read_b64_tr_b16 v[62:63], v42
	s_waitcnt lgkmcnt(12)
	v_mfma_f32_32x32x16_bf16 v[0:15], v[88:91], v[64:67], v[0:15]
	v_add_u32_e32 v40, v200, v204
	v_add_u32_e32 v42, v201, v204
	ds_read_b64_tr_b16 v[88:89], v40
	ds_read_b64_tr_b16 v[90:91], v42
	s_waitcnt lgkmcnt(12)
	v_mfma_f32_32x32x16_bf16 v[0:15], v[92:95], v[52:55], v[0:15]
	v_add_u32_e32 v40, v202, v204
	v_add_u32_e32 v42, v203, v204
	ds_read_b64_tr_b16 v[92:93], v40
	ds_read_b64_tr_b16 v[94:95], v42
	s_waitcnt lgkmcnt(12)
	v_mfma_f32_32x32x16_bf16 v[0:15], v[104:107], v[48:51], v[0:15]
	ds_read_b64_tr_b16 v[104:105], v186 offset:128
	ds_read_b64_tr_b16 v[106:107], v186 offset:4608
	s_waitcnt lgkmcnt(12)
	v_mfma_f32_32x32x16_bf16 v[0:15], v[108:111], v[36:39], v[0:15]
	ds_read_b64_tr_b16 v[108:109], v186 offset:9088
	ds_read_b64_tr_b16 v[110:111], v186 offset:13568
	s_waitcnt lgkmcnt(12)
	v_mfma_f32_32x32x16_bf16 v[0:15], v[120:123], v[32:35], v[0:15]
	ds_read_b64_tr_b16 v[120:121], v186 offset:18048
	ds_read_b64_tr_b16 v[122:123], v186 offset:22528
	s_waitcnt lgkmcnt(12)
	v_mfma_f32_32x32x16_bf16 v[0:15], v[56:59], v[20:23], v[0:15]
	ds_read_b64_tr_b16 v[56:57], v186 offset:27008
	ds_read_b64_tr_b16 v[58:59], v186 offset:31488
	s_waitcnt lgkmcnt(12)
	v_mfma_f32_32x32x16_bf16 v[0:15], v[60:63], v[16:19], v[0:15]
	ds_read_b64_tr_b16 v[60:61], v186 offset:35968
	ds_read_b64_tr_b16 v[62:63], v186 offset:40448
	s_waitcnt lgkmcnt(12)
	v_mfma_f32_32x32x16_bf16 v[0:15], v[88:91], v[28:31], v[0:15]
	ds_read_b64_tr_b16 v[88:89], v186 offset:44928
	ds_read_b64_tr_b16 v[90:91], v186 offset:49408
	s_waitcnt lgkmcnt(12)
	v_mfma_f32_32x32x16_bf16 v[0:15], v[92:95], v[24:27], v[0:15]
	ds_read_b64_tr_b16 v[92:93], v186 offset:53888
	ds_read_b64_tr_b16 v[94:95], v186 offset:58368
	s_nop 11
	v_pk_mul_f32 v[0:1], v[0:1], v[44:45] op_sel_hi:[1,0]
	v_pk_mul_f32 v[2:3], v[2:3], v[44:45] op_sel_hi:[1,0]
	v_pk_mul_f32 v[4:5], v[4:5], v[44:45] op_sel_hi:[1,0]
	v_pk_mul_f32 v[6:7], v[6:7], v[44:45] op_sel_hi:[1,0]
	v_cvt_pk_bf16_f32 v0, v0, v1
	v_cvt_pk_bf16_f32 v1, v2, v3
	v_cvt_pk_bf16_f32 v2, v4, v5
	v_cvt_pk_bf16_f32 v3, v6, v7
	s_nop 1
	v_permlane32_swap_b32_e32 v0, v2
	v_permlane32_swap_b32_e32 v1, v3
	global_store_dwordx4 v[124:125], v[0:3], off offset:64
	v_pk_mul_f32 v[8:9], v[8:9], v[44:45] op_sel_hi:[1,0]
	v_pk_mul_f32 v[10:11], v[10:11], v[44:45] op_sel_hi:[1,0]
	v_pk_mul_f32 v[12:13], v[12:13], v[44:45] op_sel_hi:[1,0]
	v_pk_mul_f32 v[14:15], v[14:15], v[44:45] op_sel_hi:[1,0]
	v_cvt_pk_bf16_f32 v4, v8, v9
	v_cvt_pk_bf16_f32 v5, v10, v11
	v_cvt_pk_bf16_f32 v6, v12, v13
	v_cvt_pk_bf16_f32 v7, v14, v15
	s_nop 1
	v_permlane32_swap_b32_e32 v4, v6
	v_permlane32_swap_b32_e32 v5, v7
	global_store_dwordx4 v[124:125], v[4:7], off offset:96
	s_nop 1
	s_waitcnt lgkmcnt(12)
	v_mfma_f32_32x32x16_bf16 v[0:15], v[104:107], v[116:119], 0
	v_add_u32_e32 v40, v187, v205
	ds_read_b64_tr_b16 v[104:105], v186 offset:62848
	ds_read_b64_tr_b16 v[106:107], v40
	s_waitcnt lgkmcnt(12)
	v_mfma_f32_32x32x16_bf16 v[0:15], v[108:111], v[112:115], v[0:15]
	v_add_u32_e32 v40, v188, v205
	v_add_u32_e32 v42, v189, v205
	ds_read_b64_tr_b16 v[108:109], v40
	ds_read_b64_tr_b16 v[110:111], v42
	s_waitcnt lgkmcnt(12)
	v_mfma_f32_32x32x16_bf16 v[0:15], v[120:123], v[100:103], v[0:15]
	v_add_u32_e32 v40, v190, v205
	v_add_u32_e32 v42, v191, v205
	ds_read_b64_tr_b16 v[120:121], v40
	ds_read_b64_tr_b16 v[122:123], v42
	s_waitcnt lgkmcnt(12)
	v_mfma_f32_32x32x16_bf16 v[0:15], v[56:59], v[96:99], v[0:15]
	v_add_u32_e32 v40, v192, v205
	v_add_u32_e32 v42, v193, v205
	ds_read_b64_tr_b16 v[56:57], v40
	ds_read_b64_tr_b16 v[58:59], v42
	s_waitcnt lgkmcnt(12)
	v_mfma_f32_32x32x16_bf16 v[0:15], v[60:63], v[84:87], v[0:15]
	v_add_u32_e32 v40, v194, v205
	v_add_u32_e32 v42, v195, v205
	ds_read_b64_tr_b16 v[60:61], v40
	ds_read_b64_tr_b16 v[62:63], v42
	s_waitcnt lgkmcnt(12)
	v_mfma_f32_32x32x16_bf16 v[0:15], v[88:91], v[80:83], v[0:15]
	v_add_u32_e32 v40, v196, v205
	v_add_u32_e32 v42, v197, v205
	ds_read_b64_tr_b16 v[88:89], v40
	ds_read_b64_tr_b16 v[90:91], v42
	s_waitcnt lgkmcnt(12)
	v_mfma_f32_32x32x16_bf16 v[0:15], v[92:95], v[68:71], v[0:15]
	v_add_u32_e32 v40, v198, v205
	v_add_u32_e32 v42, v199, v205
	ds_read_b64_tr_b16 v[92:93], v40
	ds_read_b64_tr_b16 v[94:95], v42
	s_waitcnt lgkmcnt(12)
	v_mfma_f32_32x32x16_bf16 v[0:15], v[104:107], v[64:67], v[0:15]
	v_add_u32_e32 v40, v200, v205
	v_add_u32_e32 v42, v201, v205
	ds_read_b64_tr_b16 v[104:105], v40
	ds_read_b64_tr_b16 v[106:107], v42
	s_waitcnt lgkmcnt(12)
	v_mfma_f32_32x32x16_bf16 v[0:15], v[108:111], v[52:55], v[0:15]
	v_add_u32_e32 v40, v202, v205
	v_add_u32_e32 v42, v203, v205
	ds_read_b64_tr_b16 v[108:109], v40
	ds_read_b64_tr_b16 v[110:111], v42
	s_waitcnt lgkmcnt(12)
	v_mfma_f32_32x32x16_bf16 v[0:15], v[120:123], v[48:51], v[0:15]
	ds_read_b64_tr_b16 v[120:121], v186 offset:192
	ds_read_b64_tr_b16 v[122:123], v186 offset:4672
	s_waitcnt lgkmcnt(12)
	v_mfma_f32_32x32x16_bf16 v[0:15], v[56:59], v[36:39], v[0:15]
	ds_read_b64_tr_b16 v[56:57], v186 offset:9152
	ds_read_b64_tr_b16 v[58:59], v186 offset:13632
	s_waitcnt lgkmcnt(12)
	v_mfma_f32_32x32x16_bf16 v[0:15], v[60:63], v[32:35], v[0:15]
	ds_read_b64_tr_b16 v[60:61], v186 offset:18112
	ds_read_b64_tr_b16 v[62:63], v186 offset:22592
	s_waitcnt lgkmcnt(12)
	v_mfma_f32_32x32x16_bf16 v[0:15], v[88:91], v[20:23], v[0:15]
	ds_read_b64_tr_b16 v[88:89], v186 offset:27072
	ds_read_b64_tr_b16 v[90:91], v186 offset:31552
	s_waitcnt lgkmcnt(12)
	v_mfma_f32_32x32x16_bf16 v[0:15], v[92:95], v[16:19], v[0:15]
	ds_read_b64_tr_b16 v[92:93], v186 offset:36032
	ds_read_b64_tr_b16 v[94:95], v186 offset:40512
	s_waitcnt lgkmcnt(12)
	v_mfma_f32_32x32x16_bf16 v[0:15], v[104:107], v[28:31], v[0:15]
	ds_read_b64_tr_b16 v[104:105], v186 offset:44992
	ds_read_b64_tr_b16 v[106:107], v186 offset:49472
	s_waitcnt lgkmcnt(12)
	v_mfma_f32_32x32x16_bf16 v[0:15], v[108:111], v[24:27], v[0:15]
	ds_read_b64_tr_b16 v[108:109], v186 offset:53952
	ds_read_b64_tr_b16 v[110:111], v186 offset:58432
	s_nop 11
	v_pk_mul_f32 v[0:1], v[0:1], v[44:45] op_sel_hi:[1,0]
	v_pk_mul_f32 v[2:3], v[2:3], v[44:45] op_sel_hi:[1,0]
	v_pk_mul_f32 v[4:5], v[4:5], v[44:45] op_sel_hi:[1,0]
	v_pk_mul_f32 v[6:7], v[6:7], v[44:45] op_sel_hi:[1,0]
	v_cvt_pk_bf16_f32 v0, v0, v1
	v_cvt_pk_bf16_f32 v1, v2, v3
	v_cvt_pk_bf16_f32 v2, v4, v5
	v_cvt_pk_bf16_f32 v3, v6, v7
	s_nop 1
	v_permlane32_swap_b32_e32 v0, v2
	v_permlane32_swap_b32_e32 v1, v3
	global_store_dwordx4 v[124:125], v[0:3], off offset:128
	v_pk_mul_f32 v[8:9], v[8:9], v[44:45] op_sel_hi:[1,0]
	v_pk_mul_f32 v[10:11], v[10:11], v[44:45] op_sel_hi:[1,0]
	v_pk_mul_f32 v[12:13], v[12:13], v[44:45] op_sel_hi:[1,0]
	v_pk_mul_f32 v[14:15], v[14:15], v[44:45] op_sel_hi:[1,0]
	v_cvt_pk_bf16_f32 v4, v8, v9
	v_cvt_pk_bf16_f32 v5, v10, v11
	v_cvt_pk_bf16_f32 v6, v12, v13
	v_cvt_pk_bf16_f32 v7, v14, v15
	s_nop 1
	v_permlane32_swap_b32_e32 v4, v6
	v_permlane32_swap_b32_e32 v5, v7
	global_store_dwordx4 v[124:125], v[4:7], off offset:160
	s_nop 1
	s_waitcnt lgkmcnt(12)
	v_mfma_f32_32x32x16_bf16 v[0:15], v[120:123], v[116:119], 0
	v_add_u32_e32 v40, v187, v206
	ds_read_b64_tr_b16 v[120:121], v186 offset:62912
	ds_read_b64_tr_b16 v[122:123], v40
	s_waitcnt lgkmcnt(12)
	v_mfma_f32_32x32x16_bf16 v[0:15], v[56:59], v[112:115], v[0:15]
	v_add_u32_e32 v40, v188, v206
	v_add_u32_e32 v42, v189, v206
	ds_read_b64_tr_b16 v[56:57], v40
	ds_read_b64_tr_b16 v[58:59], v42
	s_waitcnt lgkmcnt(12)
	v_mfma_f32_32x32x16_bf16 v[0:15], v[60:63], v[100:103], v[0:15]
	v_add_u32_e32 v40, v190, v206
	v_add_u32_e32 v42, v191, v206
	ds_read_b64_tr_b16 v[60:61], v40
	ds_read_b64_tr_b16 v[62:63], v42
	s_waitcnt lgkmcnt(12)
	v_mfma_f32_32x32x16_bf16 v[0:15], v[88:91], v[96:99], v[0:15]
	v_add_u32_e32 v40, v192, v206
	v_add_u32_e32 v42, v193, v206
	ds_read_b64_tr_b16 v[88:89], v40
	ds_read_b64_tr_b16 v[90:91], v42
	s_waitcnt lgkmcnt(12)
	v_mfma_f32_32x32x16_bf16 v[0:15], v[92:95], v[84:87], v[0:15]
	v_add_u32_e32 v40, v194, v206
	v_add_u32_e32 v42, v195, v206
	ds_read_b64_tr_b16 v[92:93], v40
	ds_read_b64_tr_b16 v[94:95], v42
	s_waitcnt lgkmcnt(12)
	v_mfma_f32_32x32x16_bf16 v[0:15], v[104:107], v[80:83], v[0:15]
	v_add_u32_e32 v40, v196, v206
	v_add_u32_e32 v42, v197, v206
	ds_read_b64_tr_b16 v[104:105], v40
	ds_read_b64_tr_b16 v[106:107], v42
	s_waitcnt lgkmcnt(12)
	v_mfma_f32_32x32x16_bf16 v[0:15], v[108:111], v[68:71], v[0:15]
	v_add_u32_e32 v40, v198, v206
	v_add_u32_e32 v42, v199, v206
	ds_read_b64_tr_b16 v[108:109], v40
	ds_read_b64_tr_b16 v[110:111], v42
	s_waitcnt lgkmcnt(12)
	v_mfma_f32_32x32x16_bf16 v[0:15], v[120:123], v[64:67], v[0:15]
	v_add_u32_e32 v40, v200, v206
	v_add_u32_e32 v42, v201, v206
	ds_read_b64_tr_b16 v[120:121], v40
	ds_read_b64_tr_b16 v[122:123], v42
	s_waitcnt lgkmcnt(12)
	v_mfma_f32_32x32x16_bf16 v[0:15], v[56:59], v[52:55], v[0:15]
	v_add_u32_e32 v40, v202, v206
	v_add_u32_e32 v42, v203, v206
	ds_read_b64_tr_b16 v[56:57], v40
	ds_read_b64_tr_b16 v[58:59], v42
	s_waitcnt lgkmcnt(12)
	v_mfma_f32_32x32x16_bf16 v[0:15], v[60:63], v[48:51], v[0:15]
	ds_read_b64_tr_b16 v[60:61], v186 offset:256
	ds_read_b64_tr_b16 v[62:63], v186 offset:4736
	s_waitcnt lgkmcnt(12)
	v_mfma_f32_32x32x16_bf16 v[0:15], v[88:91], v[36:39], v[0:15]
	ds_read_b64_tr_b16 v[88:89], v186 offset:9216
	ds_read_b64_tr_b16 v[90:91], v186 offset:13696
	s_waitcnt lgkmcnt(12)
	v_mfma_f32_32x32x16_bf16 v[0:15], v[92:95], v[32:35], v[0:15]
	ds_read_b64_tr_b16 v[92:93], v186 offset:18176
	ds_read_b64_tr_b16 v[94:95], v186 offset:22656
	s_waitcnt lgkmcnt(12)
	v_mfma_f32_32x32x16_bf16 v[0:15], v[104:107], v[20:23], v[0:15]
	ds_read_b64_tr_b16 v[104:105], v186 offset:27136
	ds_read_b64_tr_b16 v[106:107], v186 offset:31616
	s_waitcnt lgkmcnt(12)
	v_mfma_f32_32x32x16_bf16 v[0:15], v[108:111], v[16:19], v[0:15]
	ds_read_b64_tr_b16 v[108:109], v186 offset:36096
	ds_read_b64_tr_b16 v[110:111], v186 offset:40576
	s_waitcnt lgkmcnt(12)
	v_mfma_f32_32x32x16_bf16 v[0:15], v[120:123], v[28:31], v[0:15]
	ds_read_b64_tr_b16 v[120:121], v186 offset:45056
	ds_read_b64_tr_b16 v[122:123], v186 offset:49536
	s_waitcnt lgkmcnt(12)
	v_mfma_f32_32x32x16_bf16 v[0:15], v[56:59], v[24:27], v[0:15]
	ds_read_b64_tr_b16 v[56:57], v186 offset:54016
	ds_read_b64_tr_b16 v[58:59], v186 offset:58496
	s_nop 11
	v_pk_mul_f32 v[0:1], v[0:1], v[44:45] op_sel_hi:[1,0]
	v_pk_mul_f32 v[2:3], v[2:3], v[44:45] op_sel_hi:[1,0]
	v_pk_mul_f32 v[4:5], v[4:5], v[44:45] op_sel_hi:[1,0]
	v_pk_mul_f32 v[6:7], v[6:7], v[44:45] op_sel_hi:[1,0]
	v_cvt_pk_bf16_f32 v0, v0, v1
	v_cvt_pk_bf16_f32 v1, v2, v3
	v_cvt_pk_bf16_f32 v2, v4, v5
	v_cvt_pk_bf16_f32 v3, v6, v7
	s_nop 1
	v_permlane32_swap_b32_e32 v0, v2
	v_permlane32_swap_b32_e32 v1, v3
	global_store_dwordx4 v[124:125], v[0:3], off offset:192
	v_pk_mul_f32 v[8:9], v[8:9], v[44:45] op_sel_hi:[1,0]
	v_pk_mul_f32 v[10:11], v[10:11], v[44:45] op_sel_hi:[1,0]
	v_pk_mul_f32 v[12:13], v[12:13], v[44:45] op_sel_hi:[1,0]
	v_pk_mul_f32 v[14:15], v[14:15], v[44:45] op_sel_hi:[1,0]
	v_cvt_pk_bf16_f32 v4, v8, v9
	v_cvt_pk_bf16_f32 v5, v10, v11
	v_cvt_pk_bf16_f32 v6, v12, v13
	v_cvt_pk_bf16_f32 v7, v14, v15
	s_nop 1
	v_permlane32_swap_b32_e32 v4, v6
	v_permlane32_swap_b32_e32 v5, v7
	global_store_dwordx4 v[124:125], v[4:7], off offset:224
	s_nop 1
	s_waitcnt lgkmcnt(12)
	v_mfma_f32_32x32x16_bf16 v[0:15], v[60:63], v[116:119], 0
	v_add_u32_e32 v40, v187, v207
	ds_read_b64_tr_b16 v[60:61], v186 offset:62976
	ds_read_b64_tr_b16 v[62:63], v40
	s_waitcnt lgkmcnt(12)
	v_mfma_f32_32x32x16_bf16 v[0:15], v[88:91], v[112:115], v[0:15]
	v_add_u32_e32 v40, v188, v207
	v_add_u32_e32 v42, v189, v207
	ds_read_b64_tr_b16 v[88:89], v40
	ds_read_b64_tr_b16 v[90:91], v42
	s_waitcnt lgkmcnt(12)
	v_mfma_f32_32x32x16_bf16 v[0:15], v[92:95], v[100:103], v[0:15]
	v_add_u32_e32 v40, v190, v207
	v_add_u32_e32 v42, v191, v207
	ds_read_b64_tr_b16 v[92:93], v40
	ds_read_b64_tr_b16 v[94:95], v42
	s_waitcnt lgkmcnt(12)
	v_mfma_f32_32x32x16_bf16 v[0:15], v[104:107], v[96:99], v[0:15]
	v_add_u32_e32 v40, v192, v207
	v_add_u32_e32 v42, v193, v207
	ds_read_b64_tr_b16 v[104:105], v40
	ds_read_b64_tr_b16 v[106:107], v42
	s_waitcnt lgkmcnt(12)
	v_mfma_f32_32x32x16_bf16 v[0:15], v[108:111], v[84:87], v[0:15]
	v_add_u32_e32 v40, v194, v207
	v_add_u32_e32 v42, v195, v207
	ds_read_b64_tr_b16 v[108:109], v40
	ds_read_b64_tr_b16 v[110:111], v42
	s_waitcnt lgkmcnt(12)
	v_mfma_f32_32x32x16_bf16 v[0:15], v[120:123], v[80:83], v[0:15]
	v_add_u32_e32 v40, v196, v207
	v_add_u32_e32 v42, v197, v207
	ds_read_b64_tr_b16 v[120:121], v40
	ds_read_b64_tr_b16 v[122:123], v42
	s_waitcnt lgkmcnt(12)
	v_mfma_f32_32x32x16_bf16 v[0:15], v[56:59], v[68:71], v[0:15]
	v_add_u32_e32 v40, v198, v207
	v_add_u32_e32 v42, v199, v207
	ds_read_b64_tr_b16 v[56:57], v40
	ds_read_b64_tr_b16 v[58:59], v42
	s_waitcnt lgkmcnt(12)
	v_mfma_f32_32x32x16_bf16 v[0:15], v[60:63], v[64:67], v[0:15]
	v_add_u32_e32 v40, v200, v207
	v_add_u32_e32 v42, v201, v207
	ds_read_b64_tr_b16 v[60:61], v40
	ds_read_b64_tr_b16 v[62:63], v42
	s_waitcnt lgkmcnt(12)
	v_mfma_f32_32x32x16_bf16 v[0:15], v[88:91], v[52:55], v[0:15]
	v_add_u32_e32 v40, v202, v207
	v_add_u32_e32 v42, v203, v207
	ds_read_b64_tr_b16 v[88:89], v40
	ds_read_b64_tr_b16 v[90:91], v42
	s_waitcnt lgkmcnt(12)
	v_mfma_f32_32x32x16_bf16 v[0:15], v[92:95], v[48:51], v[0:15]
	ds_read_b64_tr_b16 v[92:93], v186 offset:320
	ds_read_b64_tr_b16 v[94:95], v186 offset:4800
	s_waitcnt lgkmcnt(12)
	v_mfma_f32_32x32x16_bf16 v[0:15], v[104:107], v[36:39], v[0:15]
	ds_read_b64_tr_b16 v[104:105], v186 offset:9280
	ds_read_b64_tr_b16 v[106:107], v186 offset:13760
	s_waitcnt lgkmcnt(12)
	v_mfma_f32_32x32x16_bf16 v[0:15], v[108:111], v[32:35], v[0:15]
	ds_read_b64_tr_b16 v[108:109], v186 offset:18240
	ds_read_b64_tr_b16 v[110:111], v186 offset:22720
	s_waitcnt lgkmcnt(12)
	v_mfma_f32_32x32x16_bf16 v[0:15], v[120:123], v[20:23], v[0:15]
	ds_read_b64_tr_b16 v[120:121], v186 offset:27200
	ds_read_b64_tr_b16 v[122:123], v186 offset:31680
	s_waitcnt lgkmcnt(12)
	v_mfma_f32_32x32x16_bf16 v[0:15], v[56:59], v[16:19], v[0:15]
	ds_read_b64_tr_b16 v[56:57], v186 offset:36160
	ds_read_b64_tr_b16 v[58:59], v186 offset:40640
	s_waitcnt lgkmcnt(12)
	v_mfma_f32_32x32x16_bf16 v[0:15], v[60:63], v[28:31], v[0:15]
	ds_read_b64_tr_b16 v[60:61], v186 offset:45120
	ds_read_b64_tr_b16 v[62:63], v186 offset:49600
	s_waitcnt lgkmcnt(12)
	v_mfma_f32_32x32x16_bf16 v[0:15], v[88:91], v[24:27], v[0:15]
	ds_read_b64_tr_b16 v[88:89], v186 offset:54080
	ds_read_b64_tr_b16 v[90:91], v186 offset:58560
	s_nop 11
	v_pk_mul_f32 v[0:1], v[0:1], v[44:45] op_sel_hi:[1,0]
	v_pk_mul_f32 v[2:3], v[2:3], v[44:45] op_sel_hi:[1,0]
	v_pk_mul_f32 v[4:5], v[4:5], v[44:45] op_sel_hi:[1,0]
	v_pk_mul_f32 v[6:7], v[6:7], v[44:45] op_sel_hi:[1,0]
	v_cvt_pk_bf16_f32 v0, v0, v1
	v_cvt_pk_bf16_f32 v1, v2, v3
	v_cvt_pk_bf16_f32 v2, v4, v5
	v_cvt_pk_bf16_f32 v3, v6, v7
	s_nop 1
	v_permlane32_swap_b32_e32 v0, v2
	v_permlane32_swap_b32_e32 v1, v3
	global_store_dwordx4 v[124:125], v[0:3], off offset:256
	v_pk_mul_f32 v[8:9], v[8:9], v[44:45] op_sel_hi:[1,0]
	v_pk_mul_f32 v[10:11], v[10:11], v[44:45] op_sel_hi:[1,0]
	v_pk_mul_f32 v[12:13], v[12:13], v[44:45] op_sel_hi:[1,0]
	v_pk_mul_f32 v[14:15], v[14:15], v[44:45] op_sel_hi:[1,0]
	v_cvt_pk_bf16_f32 v4, v8, v9
	v_cvt_pk_bf16_f32 v5, v10, v11
	v_cvt_pk_bf16_f32 v6, v12, v13
	v_cvt_pk_bf16_f32 v7, v14, v15
	s_nop 1
	v_permlane32_swap_b32_e32 v4, v6
	v_permlane32_swap_b32_e32 v5, v7
	global_store_dwordx4 v[124:125], v[4:7], off offset:288
	s_nop 1
	s_waitcnt lgkmcnt(12)
	v_mfma_f32_32x32x16_bf16 v[0:15], v[92:95], v[116:119], 0
	v_add_u32_e32 v40, v187, v208
	ds_read_b64_tr_b16 v[92:93], v186 offset:63040
	ds_read_b64_tr_b16 v[94:95], v40
	s_waitcnt lgkmcnt(12)
	v_mfma_f32_32x32x16_bf16 v[0:15], v[104:107], v[112:115], v[0:15]
	v_add_u32_e32 v40, v188, v208
	v_add_u32_e32 v42, v189, v208
	ds_read_b64_tr_b16 v[104:105], v40
	ds_read_b64_tr_b16 v[106:107], v42
	s_waitcnt lgkmcnt(12)
	v_mfma_f32_32x32x16_bf16 v[0:15], v[108:111], v[100:103], v[0:15]
	v_add_u32_e32 v40, v190, v208
	v_add_u32_e32 v42, v191, v208
	ds_read_b64_tr_b16 v[108:109], v40
	ds_read_b64_tr_b16 v[110:111], v42
	s_waitcnt lgkmcnt(12)
	v_mfma_f32_32x32x16_bf16 v[0:15], v[120:123], v[96:99], v[0:15]
	v_add_u32_e32 v40, v192, v208
	v_add_u32_e32 v42, v193, v208
	ds_read_b64_tr_b16 v[120:121], v40
	ds_read_b64_tr_b16 v[122:123], v42
	s_waitcnt lgkmcnt(12)
	v_mfma_f32_32x32x16_bf16 v[0:15], v[56:59], v[84:87], v[0:15]
	v_add_u32_e32 v40, v194, v208
	v_add_u32_e32 v42, v195, v208
	ds_read_b64_tr_b16 v[56:57], v40
	ds_read_b64_tr_b16 v[58:59], v42
	s_waitcnt lgkmcnt(12)
	v_mfma_f32_32x32x16_bf16 v[0:15], v[60:63], v[80:83], v[0:15]
	v_add_u32_e32 v40, v196, v208
	v_add_u32_e32 v42, v197, v208
	ds_read_b64_tr_b16 v[60:61], v40
	ds_read_b64_tr_b16 v[62:63], v42
	s_waitcnt lgkmcnt(12)
	v_mfma_f32_32x32x16_bf16 v[0:15], v[88:91], v[68:71], v[0:15]
	v_add_u32_e32 v40, v198, v208
	v_add_u32_e32 v42, v199, v208
	ds_read_b64_tr_b16 v[88:89], v40
	ds_read_b64_tr_b16 v[90:91], v42
	s_waitcnt lgkmcnt(12)
	v_mfma_f32_32x32x16_bf16 v[0:15], v[92:95], v[64:67], v[0:15]
	v_add_u32_e32 v40, v200, v208
	v_add_u32_e32 v42, v201, v208
	ds_read_b64_tr_b16 v[92:93], v40
	ds_read_b64_tr_b16 v[94:95], v42
	s_waitcnt lgkmcnt(12)
	v_mfma_f32_32x32x16_bf16 v[0:15], v[104:107], v[52:55], v[0:15]
	v_add_u32_e32 v40, v202, v208
	v_add_u32_e32 v42, v203, v208
	ds_read_b64_tr_b16 v[104:105], v40
	ds_read_b64_tr_b16 v[106:107], v42
	s_waitcnt lgkmcnt(12)
	v_mfma_f32_32x32x16_bf16 v[0:15], v[108:111], v[48:51], v[0:15]
	ds_read_b64_tr_b16 v[108:109], v186 offset:384
	ds_read_b64_tr_b16 v[110:111], v186 offset:4864
	s_waitcnt lgkmcnt(12)
	v_mfma_f32_32x32x16_bf16 v[0:15], v[120:123], v[36:39], v[0:15]
	ds_read_b64_tr_b16 v[120:121], v186 offset:9344
	ds_read_b64_tr_b16 v[122:123], v186 offset:13824
	s_waitcnt lgkmcnt(12)
	v_mfma_f32_32x32x16_bf16 v[0:15], v[56:59], v[32:35], v[0:15]
	ds_read_b64_tr_b16 v[56:57], v186 offset:18304
	ds_read_b64_tr_b16 v[58:59], v186 offset:22784
	s_waitcnt lgkmcnt(12)
	v_mfma_f32_32x32x16_bf16 v[0:15], v[60:63], v[20:23], v[0:15]
	ds_read_b64_tr_b16 v[60:61], v186 offset:27264
	ds_read_b64_tr_b16 v[62:63], v186 offset:31744
	s_waitcnt lgkmcnt(12)
	v_mfma_f32_32x32x16_bf16 v[0:15], v[88:91], v[16:19], v[0:15]
	ds_read_b64_tr_b16 v[88:89], v186 offset:36224
	ds_read_b64_tr_b16 v[90:91], v186 offset:40704
	s_waitcnt lgkmcnt(12)
	v_mfma_f32_32x32x16_bf16 v[0:15], v[92:95], v[28:31], v[0:15]
	ds_read_b64_tr_b16 v[92:93], v186 offset:45184
	ds_read_b64_tr_b16 v[94:95], v186 offset:49664
	s_waitcnt lgkmcnt(12)
	v_mfma_f32_32x32x16_bf16 v[0:15], v[104:107], v[24:27], v[0:15]
	ds_read_b64_tr_b16 v[104:105], v186 offset:54144
	ds_read_b64_tr_b16 v[106:107], v186 offset:58624
	s_nop 11
	v_pk_mul_f32 v[0:1], v[0:1], v[44:45] op_sel_hi:[1,0]
	v_pk_mul_f32 v[2:3], v[2:3], v[44:45] op_sel_hi:[1,0]
	v_pk_mul_f32 v[4:5], v[4:5], v[44:45] op_sel_hi:[1,0]
	v_pk_mul_f32 v[6:7], v[6:7], v[44:45] op_sel_hi:[1,0]
	v_cvt_pk_bf16_f32 v0, v0, v1
	v_cvt_pk_bf16_f32 v1, v2, v3
	v_cvt_pk_bf16_f32 v2, v4, v5
	v_cvt_pk_bf16_f32 v3, v6, v7
	s_nop 1
	v_permlane32_swap_b32_e32 v0, v2
	v_permlane32_swap_b32_e32 v1, v3
	global_store_dwordx4 v[124:125], v[0:3], off offset:320
	v_pk_mul_f32 v[8:9], v[8:9], v[44:45] op_sel_hi:[1,0]
	v_pk_mul_f32 v[10:11], v[10:11], v[44:45] op_sel_hi:[1,0]
	v_pk_mul_f32 v[12:13], v[12:13], v[44:45] op_sel_hi:[1,0]
	v_pk_mul_f32 v[14:15], v[14:15], v[44:45] op_sel_hi:[1,0]
	v_cvt_pk_bf16_f32 v4, v8, v9
	v_cvt_pk_bf16_f32 v5, v10, v11
	v_cvt_pk_bf16_f32 v6, v12, v13
	v_cvt_pk_bf16_f32 v7, v14, v15
	s_nop 1
	v_permlane32_swap_b32_e32 v4, v6
	v_permlane32_swap_b32_e32 v5, v7
	global_store_dwordx4 v[124:125], v[4:7], off offset:352
	s_nop 1
	s_waitcnt lgkmcnt(12)
	v_mfma_f32_32x32x16_bf16 v[0:15], v[108:111], v[116:119], 0
	v_add_u32_e32 v40, v187, v209
	ds_read_b64_tr_b16 v[108:109], v186 offset:63104
	ds_read_b64_tr_b16 v[110:111], v40
	s_waitcnt lgkmcnt(12)
	v_mfma_f32_32x32x16_bf16 v[0:15], v[120:123], v[112:115], v[0:15]
	v_add_u32_e32 v40, v188, v209
	v_add_u32_e32 v42, v189, v209
	ds_read_b64_tr_b16 v[120:121], v40
	ds_read_b64_tr_b16 v[122:123], v42
	s_waitcnt lgkmcnt(12)
	v_mfma_f32_32x32x16_bf16 v[0:15], v[56:59], v[100:103], v[0:15]
	v_add_u32_e32 v40, v190, v209
	v_add_u32_e32 v42, v191, v209
	ds_read_b64_tr_b16 v[56:57], v40
	ds_read_b64_tr_b16 v[58:59], v42
	s_waitcnt lgkmcnt(12)
	v_mfma_f32_32x32x16_bf16 v[0:15], v[60:63], v[96:99], v[0:15]
	v_add_u32_e32 v40, v192, v209
	v_add_u32_e32 v42, v193, v209
	ds_read_b64_tr_b16 v[60:61], v40
	ds_read_b64_tr_b16 v[62:63], v42
	s_waitcnt lgkmcnt(12)
	v_mfma_f32_32x32x16_bf16 v[0:15], v[88:91], v[84:87], v[0:15]
	v_add_u32_e32 v40, v194, v209
	v_add_u32_e32 v42, v195, v209
	ds_read_b64_tr_b16 v[88:89], v40
	ds_read_b64_tr_b16 v[90:91], v42
	s_waitcnt lgkmcnt(12)
	v_mfma_f32_32x32x16_bf16 v[0:15], v[92:95], v[80:83], v[0:15]
	v_add_u32_e32 v40, v196, v209
	v_add_u32_e32 v42, v197, v209
	ds_read_b64_tr_b16 v[92:93], v40
	ds_read_b64_tr_b16 v[94:95], v42
	s_waitcnt lgkmcnt(12)
	v_mfma_f32_32x32x16_bf16 v[0:15], v[104:107], v[68:71], v[0:15]
	v_add_u32_e32 v40, v198, v209
	v_add_u32_e32 v42, v199, v209
	ds_read_b64_tr_b16 v[104:105], v40
	ds_read_b64_tr_b16 v[106:107], v42
	s_waitcnt lgkmcnt(12)
	v_mfma_f32_32x32x16_bf16 v[0:15], v[108:111], v[64:67], v[0:15]
	v_add_u32_e32 v40, v200, v209
	v_add_u32_e32 v42, v201, v209
	ds_read_b64_tr_b16 v[108:109], v40
	ds_read_b64_tr_b16 v[110:111], v42
	s_waitcnt lgkmcnt(12)
	v_mfma_f32_32x32x16_bf16 v[0:15], v[120:123], v[52:55], v[0:15]
	v_add_u32_e32 v40, v202, v209
	v_add_u32_e32 v42, v203, v209
	ds_read_b64_tr_b16 v[120:121], v40
	ds_read_b64_tr_b16 v[122:123], v42
	s_waitcnt lgkmcnt(12)
	v_mfma_f32_32x32x16_bf16 v[0:15], v[56:59], v[48:51], v[0:15]
	ds_read_b64_tr_b16 v[56:57], v186 offset:448
	ds_read_b64_tr_b16 v[58:59], v186 offset:4928
	s_waitcnt lgkmcnt(12)
	v_mfma_f32_32x32x16_bf16 v[0:15], v[60:63], v[36:39], v[0:15]
	ds_read_b64_tr_b16 v[60:61], v186 offset:9408
	ds_read_b64_tr_b16 v[62:63], v186 offset:13888
	s_waitcnt lgkmcnt(12)
	v_mfma_f32_32x32x16_bf16 v[0:15], v[88:91], v[32:35], v[0:15]
	ds_read_b64_tr_b16 v[88:89], v186 offset:18368
	ds_read_b64_tr_b16 v[90:91], v186 offset:22848
	s_waitcnt lgkmcnt(12)
	v_mfma_f32_32x32x16_bf16 v[0:15], v[92:95], v[20:23], v[0:15]
	ds_read_b64_tr_b16 v[92:93], v186 offset:27328
	ds_read_b64_tr_b16 v[94:95], v186 offset:31808
	s_waitcnt lgkmcnt(12)
	v_mfma_f32_32x32x16_bf16 v[0:15], v[104:107], v[16:19], v[0:15]
	ds_read_b64_tr_b16 v[104:105], v186 offset:36288
	ds_read_b64_tr_b16 v[106:107], v186 offset:40768
	s_waitcnt lgkmcnt(12)
	v_mfma_f32_32x32x16_bf16 v[0:15], v[108:111], v[28:31], v[0:15]
	ds_read_b64_tr_b16 v[108:109], v186 offset:45248
	ds_read_b64_tr_b16 v[110:111], v186 offset:49728
	s_waitcnt lgkmcnt(12)
	v_mfma_f32_32x32x16_bf16 v[0:15], v[120:123], v[24:27], v[0:15]
	ds_read_b64_tr_b16 v[120:121], v186 offset:54208
	ds_read_b64_tr_b16 v[122:123], v186 offset:58688
	s_nop 11
	v_pk_mul_f32 v[0:1], v[0:1], v[44:45] op_sel_hi:[1,0]
	v_pk_mul_f32 v[2:3], v[2:3], v[44:45] op_sel_hi:[1,0]
	v_pk_mul_f32 v[4:5], v[4:5], v[44:45] op_sel_hi:[1,0]
	v_pk_mul_f32 v[6:7], v[6:7], v[44:45] op_sel_hi:[1,0]
	v_cvt_pk_bf16_f32 v0, v0, v1
	v_cvt_pk_bf16_f32 v1, v2, v3
	v_cvt_pk_bf16_f32 v2, v4, v5
	v_cvt_pk_bf16_f32 v3, v6, v7
	s_nop 1
	v_permlane32_swap_b32_e32 v0, v2
	v_permlane32_swap_b32_e32 v1, v3
	global_store_dwordx4 v[124:125], v[0:3], off offset:384
	v_pk_mul_f32 v[8:9], v[8:9], v[44:45] op_sel_hi:[1,0]
	v_pk_mul_f32 v[10:11], v[10:11], v[44:45] op_sel_hi:[1,0]
	v_pk_mul_f32 v[12:13], v[12:13], v[44:45] op_sel_hi:[1,0]
	v_pk_mul_f32 v[14:15], v[14:15], v[44:45] op_sel_hi:[1,0]
	v_cvt_pk_bf16_f32 v4, v8, v9
	v_cvt_pk_bf16_f32 v5, v10, v11
	v_cvt_pk_bf16_f32 v6, v12, v13
	v_cvt_pk_bf16_f32 v7, v14, v15
	s_nop 1
	v_permlane32_swap_b32_e32 v4, v6
	v_permlane32_swap_b32_e32 v5, v7
	global_store_dwordx4 v[124:125], v[4:7], off offset:416
	s_nop 1
	s_waitcnt lgkmcnt(12)
	v_mfma_f32_32x32x16_bf16 v[0:15], v[56:59], v[116:119], 0
	v_add_u32_e32 v40, v187, v210
	ds_read_b64_tr_b16 v[56:57], v186 offset:63168
	ds_read_b64_tr_b16 v[58:59], v40
	s_waitcnt lgkmcnt(12)
	v_mfma_f32_32x32x16_bf16 v[0:15], v[60:63], v[112:115], v[0:15]
	v_add_u32_e32 v40, v188, v210
	v_add_u32_e32 v42, v189, v210
	ds_read_b64_tr_b16 v[60:61], v40
	ds_read_b64_tr_b16 v[62:63], v42
	s_waitcnt lgkmcnt(12)
	v_mfma_f32_32x32x16_bf16 v[0:15], v[88:91], v[100:103], v[0:15]
	v_add_u32_e32 v40, v190, v210
	v_add_u32_e32 v42, v191, v210
	ds_read_b64_tr_b16 v[88:89], v40
	ds_read_b64_tr_b16 v[90:91], v42
	s_waitcnt lgkmcnt(12)
	v_mfma_f32_32x32x16_bf16 v[0:15], v[92:95], v[96:99], v[0:15]
	v_add_u32_e32 v40, v192, v210
	v_add_u32_e32 v42, v193, v210
	ds_read_b64_tr_b16 v[92:93], v40
	ds_read_b64_tr_b16 v[94:95], v42
	s_waitcnt lgkmcnt(12)
	v_mfma_f32_32x32x16_bf16 v[0:15], v[104:107], v[84:87], v[0:15]
	v_add_u32_e32 v40, v194, v210
	v_add_u32_e32 v42, v195, v210
	ds_read_b64_tr_b16 v[104:105], v40
	ds_read_b64_tr_b16 v[106:107], v42
	s_waitcnt lgkmcnt(12)
	v_mfma_f32_32x32x16_bf16 v[0:15], v[108:111], v[80:83], v[0:15]
	v_add_u32_e32 v40, v196, v210
	v_add_u32_e32 v42, v197, v210
	ds_read_b64_tr_b16 v[108:109], v40
	ds_read_b64_tr_b16 v[110:111], v42
	s_waitcnt lgkmcnt(12)
	v_mfma_f32_32x32x16_bf16 v[0:15], v[120:123], v[68:71], v[0:15]
	v_add_u32_e32 v40, v198, v210
	v_add_u32_e32 v42, v199, v210
	ds_read_b64_tr_b16 v[120:121], v40
	ds_read_b64_tr_b16 v[122:123], v42
	s_waitcnt lgkmcnt(12)
	v_mfma_f32_32x32x16_bf16 v[0:15], v[56:59], v[64:67], v[0:15]
	v_add_u32_e32 v40, v200, v210
	v_add_u32_e32 v42, v201, v210
	ds_read_b64_tr_b16 v[56:57], v40
	ds_read_b64_tr_b16 v[58:59], v42
	s_waitcnt lgkmcnt(12)
	v_mfma_f32_32x32x16_bf16 v[0:15], v[60:63], v[52:55], v[0:15]
	v_add_u32_e32 v40, v202, v210
	v_add_u32_e32 v42, v203, v210
	ds_read_b64_tr_b16 v[60:61], v40
	ds_read_b64_tr_b16 v[62:63], v42
	s_waitcnt lgkmcnt(12)
	v_mfma_f32_32x32x16_bf16 v[0:15], v[88:91], v[48:51], v[0:15]
	s_waitcnt lgkmcnt(10)
	v_mfma_f32_32x32x16_bf16 v[0:15], v[92:95], v[36:39], v[0:15]
	s_waitcnt lgkmcnt(8)
	v_mfma_f32_32x32x16_bf16 v[0:15], v[104:107], v[32:35], v[0:15]
	s_waitcnt lgkmcnt(6)
	v_mfma_f32_32x32x16_bf16 v[0:15], v[108:111], v[20:23], v[0:15]
	s_waitcnt lgkmcnt(4)
	v_mfma_f32_32x32x16_bf16 v[0:15], v[120:123], v[16:19], v[0:15]
	s_waitcnt lgkmcnt(2)
	v_mfma_f32_32x32x16_bf16 v[0:15], v[56:59], v[28:31], v[0:15]
	s_waitcnt lgkmcnt(0)
	v_mfma_f32_32x32x16_bf16 v[0:15], v[60:63], v[24:27], v[0:15]
	s_nop 11
	v_pk_mul_f32 v[0:1], v[0:1], v[44:45] op_sel_hi:[1,0]
	v_pk_mul_f32 v[2:3], v[2:3], v[44:45] op_sel_hi:[1,0]
	v_pk_mul_f32 v[4:5], v[4:5], v[44:45] op_sel_hi:[1,0]
	v_pk_mul_f32 v[6:7], v[6:7], v[44:45] op_sel_hi:[1,0]
	v_cvt_pk_bf16_f32 v0, v0, v1
	v_cvt_pk_bf16_f32 v1, v2, v3
	v_cvt_pk_bf16_f32 v2, v4, v5
	v_cvt_pk_bf16_f32 v3, v6, v7
	s_nop 1
	v_permlane32_swap_b32_e32 v0, v2
	v_permlane32_swap_b32_e32 v1, v3
	global_store_dwordx4 v[124:125], v[0:3], off offset:448
	v_pk_mul_f32 v[8:9], v[8:9], v[44:45] op_sel_hi:[1,0]
	v_pk_mul_f32 v[10:11], v[10:11], v[44:45] op_sel_hi:[1,0]
	v_pk_mul_f32 v[12:13], v[12:13], v[44:45] op_sel_hi:[1,0]
	v_pk_mul_f32 v[14:15], v[14:15], v[44:45] op_sel_hi:[1,0]
	v_cvt_pk_bf16_f32 v4, v8, v9
	v_cvt_pk_bf16_f32 v5, v10, v11
	v_cvt_pk_bf16_f32 v6, v12, v13
	v_cvt_pk_bf16_f32 v7, v14, v15
	s_nop 1
	v_permlane32_swap_b32_e32 v4, v6
	v_permlane32_swap_b32_e32 v5, v7
	global_store_dwordx4 v[124:125], v[4:7], off offset:480
	s_nop 1
	s_barrier
	s_branch .LBB0_751
